# RWKV per-chunk trims: sigmoid argument by one fma, scan operand reads merged into ds_read2st64_b64, step-B stores paired with ds_write2_b32
# speedup vs baseline: 1.0279x; 1.0160x over previous
.LBB0_421:
	s_or_b64 exec, exec, s[18:19]
	s_mul_i32 s52, s36, 0x20800
	s_xor_b64 s[76:77], s[22:23], -1
	s_lshl_b64 s[18:19], s[52:53], 2
	s_add_u32 s18, s20, s18
	v_mov_b32_e32 v6, 0xc200
	v_mov_b32_e32 v7, 0xb000
	s_addc_u32 s19, s21, s19
	v_cndmask_b32_e64 v6, v6, v7, s[16:17]
	s_lshl_b32 s16, s34, 1
	s_add_u32 s20, s20, s16
	s_addc_u32 s21, s21, 0
	s_lshl_b32 s22, s35, 2
	s_add_u32 s18, s18, s22
	s_addc_u32 s19, s19, 0
	s_add_u32 s78, s18, 0x118000
	v_readlane_b32 s18, v255, 3
	v_lshlrev_b32_e32 v4, 1, v116
	s_addc_u32 s79, s19, 0
	v_lshl_add_u32 v61, v235, 2, s18
	s_lshl_b32 s18, s37, 1
	v_and_b32_e32 v5, 14, v4
	v_lshrrev_b32_e32 v7, 2, v116
	s_add_u32 s18, s20, s18
	v_and_b32_e32 v52, 16, v7
	s_addc_u32 s19, s21, 0
	v_lshlrev_b32_e32 v16, 1, v5
	v_ashrrev_i32_e32 v87, 4, v116
	v_add_u32_e32 v64, 0, v4
	v_lshlrev_b32_e32 v67, 5, v5
	v_lshl_add_u64 v[4:5], s[18:19], 0, v[16:17]
	v_lshlrev_b32_e32 v16, 8, v52
	v_lshl_or_b32 v69, v139, 10, v16
	v_lshl_or_b32 v16, v87, 8, v122
	v_add_u32_e32 v92, 16, v87
	v_and_b32_e32 v60, 1, v116
	v_add_u32_e32 v91, 0, v16
	v_lshl_or_b32 v16, v92, 8, v122
	v_add_u32_e32 v93, 0, v16
	v_add_u32_e32 v16, 0x11200, v64
	v_cmp_eq_u32_e32 vcc, 0, v60
	v_or_b32_e32 v7, v52, v140
	v_mul_u32_u24_e32 v7, 0x90, v7
	v_cndmask_b32_e32 v98, v61, v16, vcc
	v_add_u32_e32 v16, 0x11000, v64
	v_cndmask_b32_e32 v99, v61, v16, vcc
	v_add_u32_e32 v16, 0x10e00, v64
	v_cndmask_b32_e32 v100, v61, v16, vcc
	v_add_u32_e32 v16, 0x10c00, v64
	v_cndmask_b32_e32 v101, v61, v16, vcc
	v_add_u32_e32 v16, 0x10a00, v64
	s_mov_b64 s[18:19], 0xe488000
	v_cndmask_b32_e32 v102, v61, v16, vcc
	v_add_u32_e32 v16, 0x10800, v64
	v_add3_u32 v62, 0, v6, v7
	v_or_b32_e32 v6, s38, v140
	v_lshl_add_u64 v[18:19], v[4:5], 0, s[18:19]
	s_mov_b32 s18, 0x5040100
	s_movk_i32 s20, 0xffde
	v_add_u32_e32 v97, v106, v105
	v_cndmask_b32_e32 v103, v61, v16, vcc
	v_add_u32_e32 v16, 0x10600, v64
	v_cmp_eq_u32_e64 s[16:17], 0, v6
	v_perm_b32 v7, v153, v151, s18
	v_perm_b32 v6, v149, v147, s18
	v_perm_b32 v5, v145, v143, s18
	v_perm_b32 v4, v142, v141, s18
	v_perm_b32 v11, v165, v163, s18
	v_perm_b32 v10, v162, v161, s18
	v_perm_b32 v9, v160, v159, s18
	v_perm_b32 v8, v158, v157, s18
	v_perm_b32 v15, v186, v184, s18
	v_perm_b32 v14, v182, v180, s18
	v_perm_b32 v13, v178, v176, s18
	v_perm_b32 v12, v174, v173, s18
	v_perm_b32 v27, v198, v195, s18
	v_perm_b32 v26, v194, v193, s18
	v_perm_b32 v25, v192, v191, s18
	v_perm_b32 v24, v190, v189, s18
	v_perm_b32 v35, v156, v155, s18
	v_perm_b32 v34, v154, v152, s18
	v_perm_b32 v33, v150, v148, s18
	v_perm_b32 v32, v146, v144, s18
	v_perm_b32 v39, v172, v171, s18
	v_perm_b32 v38, v170, v169, s18
	v_perm_b32 v37, v168, v167, s18
	v_perm_b32 v36, v166, v164, s18
	v_perm_b32 v43, v188, v187, s18
	v_perm_b32 v42, v185, v183, s18
	v_perm_b32 v41, v181, v179, s18
	v_perm_b32 v40, v177, v175, s18
	v_perm_b32 v47, v204, v203, s18
	v_perm_b32 v46, v202, v201, s18
	v_perm_b32 v45, v200, v199, s18
	v_perm_b32 v44, v197, v196, s18
	v_mad_u64_u32 v[58:59], s[18:19], v97, s20, v[104:105]
	v_cndmask_b32_e32 v104, v61, v16, vcc
	v_add_u32_e32 v16, 0x10400, v64
	v_cndmask_b32_e32 v105, v61, v16, vcc
	v_add_u32_e32 v16, 0x10200, v64
	v_cndmask_b32_e32 v106, v61, v16, vcc
	v_add_u32_e32 v16, 0x10000, v64
	v_cndmask_b32_e32 v107, v61, v16, vcc
	v_add_u32_e32 v16, 0xfe00, v64
	v_cndmask_b32_e32 v108, v61, v16, vcc
	v_add_u32_e32 v16, 0xfc00, v64
	v_cndmask_b32_e32 v109, v61, v16, vcc
	v_add_u32_e32 v16, 0xfa00, v64
	v_cndmask_b32_e32 v110, v61, v16, vcc
	v_add_u32_e32 v16, 0xf800, v64
	v_cndmask_b32_e32 v111, v61, v16, vcc
	v_add_u32_e32 v16, 0xf600, v64
	v_cndmask_b32_e32 v112, v61, v16, vcc
	v_add_u32_e32 v16, 0xf400, v64
	v_cndmask_b32_e32 v113, v61, v16, vcc
	v_add_u32_e32 v16, 0xf200, v64
	v_cndmask_b32_e32 v114, v61, v16, vcc
	v_add_u32_e32 v16, 0xf000, v64
	v_add_u32_e32 v94, v206, v205
	v_cndmask_b32_e32 v115, v61, v16, vcc
	v_add_u32_e32 v16, 0xee00, v64
	v_and_b32_e32 v63, 48, v116
	v_ashrrev_i32_e32 v90, 3, v116
	v_mad_u64_u32 v[52:53], s[18:19], v94, s20, v[116:117]
	v_cndmask_b32_e32 v116, v61, v16, vcc
	v_add_u32_e32 v16, 0xec00, v64
	v_add_u32_e32 v95, v234, v233
	v_cndmask_b32_e32 v122, v61, v16, vcc
	v_add_u32_e32 v16, 0xea00, v64
	v_mad_u64_u32 v[54:55], s[18:19], v95, s20, v[124:125]
	v_add_u32_e32 v96, v237, v236
	v_cndmask_b32_e32 v124, v61, v16, vcc
	v_add_u32_e32 v16, 0xe800, v64
	v_mad_u64_u32 v[56:57], s[18:19], v96, s20, v[126:127]
	v_cndmask_b32_e32 v126, v61, v16, vcc
	v_add_u32_e32 v16, 0xe600, v64
	v_lshl_add_u32 v88, v140, 4, 0
	v_cndmask_b32_e32 v139, v61, v16, vcc
	v_add_u32_e32 v16, 0xe400, v64
	v_mad_i32_i24 v68, v140, -12, v88
	v_cndmask_b32_e32 v140, v61, v16, vcc
	v_add_u32_e32 v16, 0xe200, v64
	v_cndmask_b32_e32 v141, v61, v16, vcc
	v_add_u32_e32 v16, 0xe000, v64
	v_cndmask_b32_e32 v142, v61, v16, vcc
	v_add_u32_e32 v16, 0xde00, v64
	v_cndmask_b32_e32 v143, v61, v16, vcc
	v_add_u32_e32 v16, 0xdc00, v64
	v_cndmask_b32_e32 v144, v61, v16, vcc
	v_add_u32_e32 v16, 0xda00, v64
	v_cndmask_b32_e32 v145, v61, v16, vcc
	v_add_u32_e32 v16, 0xd800, v64
	v_cndmask_b32_e32 v146, v61, v16, vcc
	v_add_u32_e32 v16, 0xd600, v64
	v_cndmask_b32_e32 v147, v61, v16, vcc
	v_and_b32_e32 v16, -16, v52
	v_add_u32_e32 v65, 0xd400, v64
	v_cmp_ne_u32_e64 s[18:19], 16, v16
	v_lshl_add_u32 v16, v94, 6, 0
	v_lshlrev_b32_e32 v53, 5, v52
	s_mov_b32 s28, 0x9c00
	s_movk_i32 s29, 0xc0
	s_movk_i32 s30, 0xff90
	v_cndmask_b32_e32 v148, v61, v65, vcc
	v_add3_u32 v55, v16, v53, s28
	v_mad_u64_u32 v[60:61], s[20:21], v94, s29, v[16:17]
	v_mul_lo_u32 v16, v94, s30
	v_lshlrev_b32_e32 v59, 4, v52
	v_add3_u32 v59, v60, v16, v59
	v_and_b32_e32 v16, -16, v54
	v_cmp_ne_u32_e64 s[20:21], 16, v16
	v_lshl_add_u32 v16, v95, 6, 0
	v_add_u32_e32 v53, v60, v53
	v_lshlrev_b32_e32 v64, 5, v54
	v_mad_u64_u32 v[60:61], s[22:23], v95, s29, v[16:17]
	v_add3_u32 v65, v16, v64, s28
	v_mul_lo_u32 v16, v95, s30
	v_lshlrev_b32_e32 v61, 4, v54
	v_add3_u32 v71, v60, v16, v61
	v_and_b32_e32 v16, -16, v56
	v_cmp_ne_u32_e64 s[22:23], 16, v16
	v_lshl_add_u32 v16, v96, 6, 0
	v_add_u32_e32 v64, v60, v64
	v_lshlrev_b32_e32 v72, 5, v56
	v_mad_u64_u32 v[60:61], s[24:25], v96, s29, v[16:17]
	v_add3_u32 v82, v16, v72, s28
	v_mul_lo_u32 v16, v96, s30
	v_lshlrev_b32_e32 v61, 4, v56
	v_add3_u32 v158, v60, v16, v61
	v_and_b32_e32 v16, -16, v58
	v_cmp_ne_u32_e64 s[24:25], 16, v16
	v_lshl_add_u32 v16, v97, 6, 0
	v_add_u32_e32 v83, v60, v72
	v_lshlrev_b32_e32 v72, 5, v58
	v_mad_u64_u32 v[60:61], s[26:27], v97, s29, v[16:17]
	v_add3_u32 v152, v16, v72, s28
	v_mul_lo_u32 v16, v97, s30
	v_lshlrev_b32_e32 v61, 4, v58
	v_add3_u32 v159, v60, v16, v61
	v_lshl_add_u32 v16, v86, 6, 0
	v_add_u32_e32 v153, v60, v72
	v_lshlrev_b32_e32 v72, 5, v84
	v_mad_u64_u32 v[60:61], s[26:27], v86, s29, v[16:17]
	v_add3_u32 v155, v16, v72, s28
	v_add_u32_e32 v16, v60, v72
	v_mul_lo_u32 v61, v86, s30
	v_lshlrev_b32_e32 v72, 4, v84
	v_mov_b32_e32 v149, s40
	v_mov_b32_e32 v150, s41
	v_cmp_gt_u32_e64 s[26:27], 32, v52
	v_add3_u32 v160, v60, v61, v72
	v_mov_b32_e32 v80, s42
	v_mov_b32_e32 v81, s34
	v_cmp_gt_i32_e32 vcc, 8, v52
	v_cndmask_b32_e64 v61, v149, v150, s[26:27]
	v_mov_b32_e32 v151, s39
	v_cmp_gt_u32_e64 s[26:27], 24, v52
	v_cndmask_b32_e32 v60, v80, v81, vcc
	v_cmp_gt_i32_e64 s[28:29], 16, v52
	v_cndmask_b32_e64 v61, v61, v151, s[26:27]
	v_cmp_gt_u32_e64 s[30:31], 32, v54
	v_cndmask_b32_e64 v60, v61, v60, s[28:29]
	v_lshl_add_u32 v60, v52, 3, v60
	v_ashrrev_i32_e32 v61, 31, v60
	v_lshl_add_u64 v[72:73], v[60:61], 1, s[58:59]
	v_cmp_gt_i32_e64 s[28:29], 8, v54
	v_cndmask_b32_e64 v61, v149, v150, s[30:31]
	v_cmp_gt_u32_e64 s[30:31], 24, v54
	v_cndmask_b32_e64 v60, v80, v81, s[28:29]
	v_cmp_gt_i32_e64 s[34:35], 16, v54
	v_cndmask_b32_e64 v61, v61, v151, s[30:31]
	v_cmp_gt_u32_e64 s[36:37], 32, v56
	v_cndmask_b32_e64 v60, v61, v60, s[34:35]
	v_lshl_add_u32 v60, v54, 3, v60
	v_ashrrev_i32_e32 v61, 31, v60
	v_lshl_add_u64 v[74:75], v[60:61], 1, s[58:59]
	v_cmp_gt_i32_e64 s[34:35], 8, v56
	v_cndmask_b32_e64 v61, v149, v150, s[36:37]
	v_cmp_gt_u32_e64 s[36:37], 24, v56
	v_cndmask_b32_e64 v60, v80, v81, s[34:35]
	v_cmp_gt_i32_e64 s[38:39], 16, v56
	v_cndmask_b32_e64 v61, v61, v151, s[36:37]
	v_cmp_gt_u32_e64 s[40:41], 32, v58
	v_cndmask_b32_e64 v60, v61, v60, s[38:39]
	v_lshl_add_u32 v60, v56, 3, v60
	v_ashrrev_i32_e32 v61, 31, v60
	v_lshl_add_u64 v[76:77], v[60:61], 1, s[58:59]
	v_cmp_gt_i32_e64 s[38:39], 8, v58
	v_cndmask_b32_e64 v61, v149, v150, s[40:41]
	v_cmp_gt_u32_e64 s[40:41], 24, v58
	v_cndmask_b32_e64 v60, v80, v81, s[38:39]
	v_cmp_gt_i32_e64 s[42:43], 16, v58
	v_cndmask_b32_e64 v61, v61, v151, s[40:41]
	v_cmp_gt_u32_e64 s[44:45], 32, v84
	v_cndmask_b32_e64 v60, v61, v60, s[42:43]
	v_lshl_add_u32 v60, v58, 3, v60
	v_ashrrev_i32_e32 v61, 31, v60
	v_lshl_add_u64 v[78:79], v[60:61], 1, s[58:59]
	v_cmp_gt_i32_e64 s[42:43], 8, v84
	v_cndmask_b32_e64 v61, v149, v150, s[44:45]
	v_cmp_gt_u32_e64 s[44:45], 24, v84
	v_cndmask_b32_e64 v60, v80, v81, s[42:43]
	v_cmp_gt_i32_e64 s[48:49], 16, v84
	v_cndmask_b32_e64 v61, v61, v151, s[44:45]
	v_add_u32_e32 v57, 0x1f00, v53
	v_cndmask_b32_e64 v60, v61, v60, s[48:49]
	v_cmp_gt_u32_e64 s[48:49], 16, v52
	v_add_u32_e32 v70, 0x1f00, v64
	v_add_u32_e32 v85, 0x1f00, v83
	v_cndmask_b32_e64 v52, v55, v57, s[48:49]
	v_cndmask_b32_e32 v149, v52, v53, vcc
	v_cmp_gt_u32_e32 vcc, 16, v54
	v_add_u32_e32 v154, 0x1f00, v153
	v_add_u32_e32 v156, 0x1f00, v16
	v_cndmask_b32_e32 v53, v65, v70, vcc
	v_cmp_gt_u32_e32 vcc, 16, v56
	v_lshl_add_u32 v60, v84, 3, v60
	v_mov_b32_e32 v57, 0xc080
	v_cndmask_b32_e32 v54, v82, v85, vcc
	v_cmp_gt_u32_e32 vcc, 16, v58
	v_lshl_add_u32 v66, v90, 9, 0
	v_ashrrev_i32_e32 v61, 31, v60
	v_cndmask_b32_e32 v55, v152, v154, vcc
	v_cmp_gt_u32_e32 vcc, 16, v84
	v_cndmask_b32_e64 v52, v57, v254, s[26:27]
	v_cndmask_b32_e64 v150, v53, v64, s[28:29]
	v_cndmask_b32_e32 v56, v155, v156, vcc
	v_cndmask_b32_e64 v53, v57, v254, s[30:31]
	v_cndmask_b32_e64 v151, v54, v83, s[34:35]
	v_cndmask_b32_e64 v54, v57, v254, s[36:37]
	v_cndmask_b32_e64 v152, v55, v153, s[38:39]
	v_cndmask_b32_e64 v55, v57, v254, s[40:41]
	v_cndmask_b32_e64 v153, v56, v16, s[42:43]
	v_cndmask_b32_e64 v56, v57, v254, s[44:45]
	v_mov_b32_e32 v16, v17
	v_lshl_add_u32 v89, v87, 2, 0
	v_lshl_add_u64 v[80:81], v[60:61], 1, s[58:59]
	s_mov_b32 s34, -8
	v_add_u32_e32 v154, v62, v63
	v_add_u32_e32 v155, v66, v67
	v_add_u32_e32 v156, v59, v52
	v_add_u32_e32 v157, v71, v53
	v_add_u32_e32 v158, v158, v54
	v_add_u32_e32 v159, v159, v55
	v_add_u32_e32 v160, v160, v56
	v_add_u32_e32 v161, v68, v69
	v_mov_b64_e32 v[82:83], v[16:17]
	v_mov_b64_e32 v[84:85], v[16:17]
	v_mov_b32_e32 v52, v232
	v_mov_b32_e32 v53, v231
	v_mov_b32_e32 v54, v230
	v_mov_b32_e32 v55, v207
	s_waitcnt lgkmcnt(0)
	s_barrier
	v_mad_u64_u32 v[218:219], s[26:27], v94, s83, v[72:73]
	v_mad_u64_u32 v[220:221], s[26:27], v95, s83, v[74:75]
	v_mad_u64_u32 v[222:223], s[26:27], v96, s83, v[76:77]
	v_mad_u64_u32 v[244:245], s[26:27], v97, s83, v[78:79]
	v_mad_u64_u32 v[246:247], s[26:27], v86, s83, v[80:81]
	v_and_b32_e32 v98, 31, v119
	v_lshlrev_b32_e32 v98, 3, v98
	v_lshrrev_b32_e32 v99, 5, v119
	s_lshl_b32 s26, s32, 3
	v_add_u32_e32 v99, s26, v99
	v_lshl_add_u32 v99, v99, 2, v228
	v_add_u32_e32 v99, 0x6000, v99
	v_lshrrev_b32_e32 v100, 1, v119
	v_lshlrev_b32_e32 v100, 2, v100
	v_add_u32_e32 v100, 0xd400, v100
	v_lshrrev_b32_e32 v101, 3, v119
	v_lshlrev_b32_e32 v101, 9, v101
	v_and_b32_e32 v102, 7, v119
	v_lshl_add_u32 v101, v102, 6, v101
	v_add_u32_e32 v101, 0xd400, v101
	v_sub_u32_e32 v102, s26, v102
	v_lshlrev_b32_e32 v102, 1, v102
	v_ashrrev_i32_e32 v103, 31, v102
	v_lshl_add_u64 v[102:103], v[18:19], 0, v[102:103]
	s_load_dwordx2 s[26:27], s[84:85], 0x120
	v_lshrrev_b32_e32 v60, 3, v119
	v_and_b32_e32 v61, 7, v119
	v_mov_b32_e32 v62, s82
	v_add_u32_e32 v62, 0xffffff80, v62
	v_bfe_u32 v63, v62, 2, 3
	v_lshlrev_b32_e32 v63, 6, v63
	v_lshrrev_b32_e32 v64, 5, v62
	v_lshlrev_b32_e32 v64, 6, v64
	v_and_b32_e32 v65, 3, v62
	v_lshlrev_b32_e32 v65, 4, v65
	v_lshl_add_u32 v66, v61, 3, v63
	v_lshl_add_u32 v67, v61, 3, v64
	v_add_u32_e32 v67, 0x600, v67
	v_and_b32_e32 v68, 1, v119
	v_lshl_add_u32 v69, v68, 3, v63
	v_add_u32_e32 v69, v69, v65
	v_add_u32_e32 v69, 0x400, v69
	v_mul_u32_u24_e32 v70, 0x1200, v60
	v_lshrrev_b32_e32 v71, 1, v119
	v_mul_u32_u24_e32 v162, 0x1200, v71
	s_waitcnt lgkmcnt(0)
	s_add_u32 s26, s26, 0x6aa8000
	s_addc_u32 s27, s27, 0
	v_lshl_add_u32 v16, v66, 1, v70
	v_lshl_add_u64 v[218:219], v[16:17], 0, s[26:27]
	v_add_u32_e32 v16, 0x400, v16
	v_lshl_add_u64 v[220:221], v[16:17], 0, s[26:27]
	v_lshl_add_u32 v16, v67, 1, v70
	v_lshl_add_u64 v[222:223], v[16:17], 0, s[26:27]
	v_add_u32_e32 v16, 0x100, v16
	v_lshl_add_u64 v[244:245], v[16:17], 0, s[26:27]
	v_lshl_add_u32 v16, v69, 1, v162
	v_lshl_add_u64 v[246:247], v[16:17], 0, s[26:27]
	v_lshlrev_b32_e32 v149, 8, v60
	v_lshl_add_u32 v149, v61, 5, v149
	v_add_u32_e32 v150, 0x2000, v149
	v_mul_u32_u24_e32 v156, 0x90, v60
	v_lshl_add_u32 v156, v61, 4, v156
	v_add_u32_e32 v156, 0xb000, v156
	v_add_u32_e32 v157, 0x1200, v156
	v_lshlrev_b32_e32 v151, 6, v71
	v_lshl_add_u32 v151, v68, 5, v151
	v_add_u32_e32 v151, 0xa000, v151
	v_mul_f32_e32 v117, s73, v117
	v_mul_f32_e32 v121, s73, v121
	v_mul_f32_e32 v123, s73, v123
	v_mul_f32_e32 v125, s73, v125
	v_add_u32_e32 v153, 0x100, v98
	v_add_u32_e32 v152, 0x8000, v161
	v_add_u32_e32 v158, 0x4000, v161
	s_branch .LBB0_424

.LBB0_424:
	ds_read_b128 v[56:59], v154
	ds_read_b128 v[162:165], v154 offset:64
	s_waitcnt lgkmcnt(1)
	v_mfma_f32_16x16x32_bf16 v[68:71], v[56:59], v[4:7], 0
	v_mfma_f32_16x16x32_bf16 v[64:67], v[56:59], v[8:11], 0
	v_mfma_f32_16x16x32_bf16 v[60:63], v[56:59], v[12:15], 0
	v_mfma_f32_16x16x32_bf16 v[166:169], v[56:59], v[24:27], 0
	s_waitcnt lgkmcnt(0)
	v_mfma_f32_16x16x32_bf16 v[68:71], v[162:165], v[32:35], v[68:71]
	v_mfma_f32_16x16x32_bf16 v[64:67], v[162:165], v[36:39], v[64:67]
	v_mfma_f32_16x16x32_bf16 v[60:63], v[162:165], v[40:43], v[60:63]
	v_mfma_f32_16x16x32_bf16 v[166:169], v[162:165], v[44:47], v[166:169]
	s_nop 7
	v_fma_f32 v170, v68, s73, v117
	v_fma_f32 v171, v69, s73, v117
	v_fma_f32 v172, v70, s73, v117
	v_fma_f32 v173, v71, s73, v117
	v_fma_f32 v174, v64, s73, v121
	v_fma_f32 v175, v65, s73, v121
	v_fma_f32 v176, v66, s73, v121
	v_fma_f32 v177, v67, s73, v121
	v_fma_f32 v178, v60, s73, v123
	v_fma_f32 v179, v61, s73, v123
	v_fma_f32 v180, v62, s73, v123
	v_fma_f32 v181, v63, s73, v123
	v_fma_f32 v182, v166, s73, v125
	v_fma_f32 v183, v167, s73, v125
	v_fma_f32 v184, v168, s73, v125
	v_fma_f32 v185, v169, s73, v125
	v_exp_f32_e32 v170, v170
	v_exp_f32_e32 v171, v171
	v_exp_f32_e32 v172, v172
	v_exp_f32_e32 v173, v173
	v_exp_f32_e32 v174, v174
	v_exp_f32_e32 v175, v175
	v_exp_f32_e32 v176, v176
	v_exp_f32_e32 v177, v177
	v_exp_f32_e32 v178, v178
	v_exp_f32_e32 v179, v179
	v_exp_f32_e32 v180, v180
	v_exp_f32_e32 v181, v181
	v_exp_f32_e32 v182, v182
	v_exp_f32_e32 v183, v183
	v_exp_f32_e32 v184, v184
	v_exp_f32_e32 v185, v185
	v_add_f32_e32 v170, 1.0, v170
	v_add_f32_e32 v171, 1.0, v171
	v_add_f32_e32 v172, 1.0, v172
	v_add_f32_e32 v173, 1.0, v173
	v_add_f32_e32 v174, 1.0, v174
	v_add_f32_e32 v175, 1.0, v175
	v_add_f32_e32 v176, 1.0, v176
	v_add_f32_e32 v177, 1.0, v177
	v_add_f32_e32 v178, 1.0, v178
	v_add_f32_e32 v179, 1.0, v179
	v_add_f32_e32 v180, 1.0, v180
	v_add_f32_e32 v181, 1.0, v181
	v_add_f32_e32 v182, 1.0, v182
	v_add_f32_e32 v183, 1.0, v183
	v_add_f32_e32 v184, 1.0, v184
	v_add_f32_e32 v185, 1.0, v185
	v_rcp_f32_e32 v170, v170
	v_rcp_f32_e32 v171, v171
	v_rcp_f32_e32 v172, v172
	v_rcp_f32_e32 v173, v173
	v_rcp_f32_e32 v174, v174
	v_rcp_f32_e32 v175, v175
	v_rcp_f32_e32 v176, v176
	v_rcp_f32_e32 v177, v177
	v_rcp_f32_e32 v178, v178
	v_rcp_f32_e32 v179, v179
	v_rcp_f32_e32 v180, v180
	v_rcp_f32_e32 v181, v181
	v_rcp_f32_e32 v182, v182
	v_rcp_f32_e32 v183, v183
	v_rcp_f32_e32 v184, v184
	v_rcp_f32_e32 v185, v185
	s_and_b64 vcc, exec, s[4:5]
	s_cbranch_vccz .Lrb_p0
	ds_write2_b32 v152, v170, v171 offset0:0 offset1:64
	ds_write2_b32 v152, v172, v173 offset0:128 offset1:192
	ds_write2_b32 v152, v174, v175 offset0:16 offset1:80
	ds_write2_b32 v152, v176, v177 offset0:144 offset1:208
	ds_write2_b32 v152, v178, v179 offset0:32 offset1:96
	ds_write2_b32 v152, v180, v181 offset0:160 offset1:224
	ds_write2_b32 v152, v182, v183 offset0:48 offset1:112
	ds_write2_b32 v152, v184, v185 offset0:176 offset1:240
	s_branch .Lrb_done
.Lrb_p0:
	v_mul_f32_e32 v170, 0xbf1b4598, v170
	v_mul_f32_e32 v171, 0xbf1b4598, v171
	v_mul_f32_e32 v172, 0xbf1b4598, v172
	v_mul_f32_e32 v173, 0xbf1b4598, v173
	v_mul_f32_e32 v174, 0xbf1b4598, v174
	v_mul_f32_e32 v175, 0xbf1b4598, v175
	v_mul_f32_e32 v176, 0xbf1b4598, v176
	v_mul_f32_e32 v177, 0xbf1b4598, v177
	v_mul_f32_e32 v178, 0xbf1b4598, v178
	v_mul_f32_e32 v179, 0xbf1b4598, v179
	v_mul_f32_e32 v180, 0xbf1b4598, v180
	v_mul_f32_e32 v181, 0xbf1b4598, v181
	v_mul_f32_e32 v182, 0xbf1b4598, v182
	v_mul_f32_e32 v183, 0xbf1b4598, v183
	v_mul_f32_e32 v184, 0xbf1b4598, v184
	v_mul_f32_e32 v185, 0xbf1b4598, v185
	v_mul_f32_e32 v170, 0x3fb8aa3b, v170
	v_mul_f32_e32 v171, 0x3fb8aa3b, v171
	v_mul_f32_e32 v172, 0x3fb8aa3b, v172
	v_mul_f32_e32 v173, 0x3fb8aa3b, v173
	v_mul_f32_e32 v174, 0x3fb8aa3b, v174
	v_mul_f32_e32 v175, 0x3fb8aa3b, v175
	v_mul_f32_e32 v176, 0x3fb8aa3b, v176
	v_mul_f32_e32 v177, 0x3fb8aa3b, v177
	v_mul_f32_e32 v178, 0x3fb8aa3b, v178
	v_mul_f32_e32 v179, 0x3fb8aa3b, v179
	v_mul_f32_e32 v180, 0x3fb8aa3b, v180
	v_mul_f32_e32 v181, 0x3fb8aa3b, v181
	v_mul_f32_e32 v182, 0x3fb8aa3b, v182
	v_mul_f32_e32 v183, 0x3fb8aa3b, v183
	v_mul_f32_e32 v184, 0x3fb8aa3b, v184
	v_mul_f32_e32 v185, 0x3fb8aa3b, v185
	v_exp_f32_e32 v170, v170
	v_exp_f32_e32 v171, v171
	v_exp_f32_e32 v172, v172
	v_exp_f32_e32 v173, v173
	v_exp_f32_e32 v174, v174
	v_exp_f32_e32 v175, v175
	v_exp_f32_e32 v176, v176
	v_exp_f32_e32 v177, v177
	v_exp_f32_e32 v178, v178
	v_exp_f32_e32 v179, v179
	v_exp_f32_e32 v180, v180
	v_exp_f32_e32 v181, v181
	v_exp_f32_e32 v182, v182
	v_exp_f32_e32 v183, v183
	v_exp_f32_e32 v184, v184
	v_exp_f32_e32 v185, v185
	ds_write2_b32 v158, v170, v171 offset0:0 offset1:64
	ds_write2_b32 v158, v172, v173 offset0:128 offset1:192
	ds_write2_b32 v158, v174, v175 offset0:16 offset1:80
	ds_write2_b32 v158, v176, v177 offset0:144 offset1:208
	ds_write2_b32 v158, v178, v179 offset0:32 offset1:96
	ds_write2_b32 v158, v180, v181 offset0:160 offset1:224
	ds_write2_b32 v158, v182, v183 offset0:48 offset1:112
	ds_write2_b32 v158, v184, v185 offset0:176 offset1:240

.LBB0_514:
	s_andn2_b64 vcc, exec, s[62:63]
	s_cbranch_vccnz .Lrs_fwd
	ds_read2st64_b64 v[162:165], v153 offset0:63 offset1:47
	ds_read2st64_b64 v[166:169], v153 offset0:31 offset1:79
	ds_read_b32 v170, v99 offset:1984
	ds_read2st64_b64 v[174:177], v98 offset0:63 offset1:47
	ds_read2st64_b64 v[178:181], v98 offset0:31 offset1:79
	ds_read_b32 v182, v99 offset:1920
	ds_read_b64 v[186:187], v98 offset:7936
	s_waitcnt lgkmcnt(4)
	v_pk_mul_f32 v[190:191], v[82:83], v[162:163]
	v_add_f32_e32 v196, v190, v191
	v_pk_mul_f32 v[194:195], v[82:83], v[164:165]
	s_nop 0
	v_add_f32_dpp v196, v196, v196 quad_perm:[1,0,3,2] row_mask:0xf bank_mask:0xf bound_ctrl:1
	v_pk_fma_f32 v[194:195], v[170:171], v[166:167], v[194:195] op_sel_hi:[0,1,1]
	s_nop 0
	v_add_f32_dpp v196, v196, v196 quad_perm:[2,3,0,1] row_mask:0xf bank_mask:0xf bound_ctrl:1
	s_nop 1
	v_add_f32_dpp v196, v196, v196 row_half_mirror row_mask:0xf bank_mask:0xf bound_ctrl:1
	s_nop 1
	v_add_f32_dpp v196, v196, v196 row_mirror row_mask:0xf bank_mask:0xf bound_ctrl:1
	v_mov_b32_e32 v197, v196
	s_nop 1
	v_permlane16_swap_b32_e32 v196, v197
	v_add_f32_e32 v196, v196, v197
	v_pk_fma_f32 v[82:83], v[196:197], v[168:169], v[194:195] op_sel_hi:[0,1,1] neg_lo:[1,0,0] neg_hi:[1,0,0]
	ds_read2st64_b64 v[162:165], v153 offset0:62 offset1:46
	ds_read2st64_b64 v[166:169], v153 offset0:30 offset1:78
	ds_read_b32 v170, v99 offset:1856
	ds_read_b64 v[188:189], v98 offset:7680
	s_waitcnt lgkmcnt(4)
	v_pk_mul_f32 v[190:191], v[82:83], v[174:175]
	v_add_f32_e32 v196, v190, v191
	v_pk_mul_f32 v[192:193], v[82:83], v[186:187]
	v_pk_mul_f32 v[194:195], v[82:83], v[176:177]
	v_add_f32_dpp v196, v196, v196 quad_perm:[1,0,3,2] row_mask:0xf bank_mask:0xf bound_ctrl:1
	v_add_f32_e32 v198, v192, v193
	v_pk_fma_f32 v[194:195], v[182:183], v[178:179], v[194:195] op_sel_hi:[0,1,1]
	v_add_f32_dpp v196, v196, v196 quad_perm:[2,3,0,1] row_mask:0xf bank_mask:0xf bound_ctrl:1
	v_add_f32_dpp v198, v198, v198 quad_perm:[1,0,3,2] row_mask:0xf bank_mask:0xf bound_ctrl:1
	ds_write_b32 v100, v198 offset:15872
	v_add_f32_dpp v196, v196, v196 row_half_mirror row_mask:0xf bank_mask:0xf bound_ctrl:1
	s_nop 1
	v_add_f32_dpp v196, v196, v196 row_mirror row_mask:0xf bank_mask:0xf bound_ctrl:1
	v_mov_b32_e32 v197, v196
	s_nop 1
	v_permlane16_swap_b32_e32 v196, v197
	v_add_f32_e32 v196, v196, v197
	v_pk_fma_f32 v[82:83], v[196:197], v[180:181], v[194:195] op_sel_hi:[0,1,1] neg_lo:[1,0,0] neg_hi:[1,0,0]
	ds_read2st64_b64 v[174:177], v98 offset0:62 offset1:46
	ds_read2st64_b64 v[178:181], v98 offset0:30 offset1:78
	ds_read_b32 v182, v99 offset:1792
	ds_read_b64 v[186:187], v98 offset:7424
	s_waitcnt lgkmcnt(5)
	v_pk_mul_f32 v[190:191], v[82:83], v[162:163]
	v_add_f32_e32 v196, v190, v191
	v_pk_mul_f32 v[192:193], v[82:83], v[188:189]
	v_pk_mul_f32 v[194:195], v[82:83], v[164:165]
	v_add_f32_dpp v196, v196, v196 quad_perm:[1,0,3,2] row_mask:0xf bank_mask:0xf bound_ctrl:1
	v_add_f32_e32 v198, v192, v193
	v_pk_fma_f32 v[194:195], v[170:171], v[166:167], v[194:195] op_sel_hi:[0,1,1]
	v_add_f32_dpp v196, v196, v196 quad_perm:[2,3,0,1] row_mask:0xf bank_mask:0xf bound_ctrl:1
	v_add_f32_dpp v198, v198, v198 quad_perm:[1,0,3,2] row_mask:0xf bank_mask:0xf bound_ctrl:1
	ds_write_b32 v100, v198 offset:15360
	v_add_f32_dpp v196, v196, v196 row_half_mirror row_mask:0xf bank_mask:0xf bound_ctrl:1
	s_nop 1
	v_add_f32_dpp v196, v196, v196 row_mirror row_mask:0xf bank_mask:0xf bound_ctrl:1
	v_mov_b32_e32 v197, v196
	s_nop 1
	v_permlane16_swap_b32_e32 v196, v197
	v_add_f32_e32 v196, v196, v197
	v_pk_fma_f32 v[82:83], v[196:197], v[168:169], v[194:195] op_sel_hi:[0,1,1] neg_lo:[1,0,0] neg_hi:[1,0,0]
	ds_read2st64_b64 v[162:165], v153 offset0:61 offset1:45
	ds_read2st64_b64 v[166:169], v153 offset0:29 offset1:77
	ds_read_b32 v170, v99 offset:1728
	ds_read_b64 v[188:189], v98 offset:7168
	s_waitcnt lgkmcnt(5)
	v_pk_mul_f32 v[190:191], v[82:83], v[174:175]
	v_add_f32_e32 v196, v190, v191
	v_pk_mul_f32 v[192:193], v[82:83], v[186:187]
	v_pk_mul_f32 v[194:195], v[82:83], v[176:177]
	v_add_f32_dpp v196, v196, v196 quad_perm:[1,0,3,2] row_mask:0xf bank_mask:0xf bound_ctrl:1
	v_add_f32_e32 v198, v192, v193
	v_pk_fma_f32 v[194:195], v[182:183], v[178:179], v[194:195] op_sel_hi:[0,1,1]
	v_add_f32_dpp v196, v196, v196 quad_perm:[2,3,0,1] row_mask:0xf bank_mask:0xf bound_ctrl:1
	v_add_f32_dpp v198, v198, v198 quad_perm:[1,0,3,2] row_mask:0xf bank_mask:0xf bound_ctrl:1
	ds_write_b32 v100, v198 offset:14848
	v_add_f32_dpp v196, v196, v196 row_half_mirror row_mask:0xf bank_mask:0xf bound_ctrl:1
	s_nop 1
	v_add_f32_dpp v196, v196, v196 row_mirror row_mask:0xf bank_mask:0xf bound_ctrl:1
	v_mov_b32_e32 v197, v196
	s_nop 1
	v_permlane16_swap_b32_e32 v196, v197
	v_add_f32_e32 v196, v196, v197
	v_pk_fma_f32 v[82:83], v[196:197], v[180:181], v[194:195] op_sel_hi:[0,1,1] neg_lo:[1,0,0] neg_hi:[1,0,0]
	ds_read2st64_b64 v[174:177], v98 offset0:61 offset1:45
	ds_read2st64_b64 v[178:181], v98 offset0:29 offset1:77
	ds_read_b32 v182, v99 offset:1664
	ds_read_b64 v[186:187], v98 offset:6912
	s_waitcnt lgkmcnt(5)
	v_pk_mul_f32 v[190:191], v[82:83], v[162:163]
	v_add_f32_e32 v196, v190, v191
	v_pk_mul_f32 v[192:193], v[82:83], v[188:189]
	v_pk_mul_f32 v[194:195], v[82:83], v[164:165]
	v_add_f32_dpp v196, v196, v196 quad_perm:[1,0,3,2] row_mask:0xf bank_mask:0xf bound_ctrl:1
	v_add_f32_e32 v198, v192, v193
	v_pk_fma_f32 v[194:195], v[170:171], v[166:167], v[194:195] op_sel_hi:[0,1,1]
	v_add_f32_dpp v196, v196, v196 quad_perm:[2,3,0,1] row_mask:0xf bank_mask:0xf bound_ctrl:1
	v_add_f32_dpp v198, v198, v198 quad_perm:[1,0,3,2] row_mask:0xf bank_mask:0xf bound_ctrl:1
	ds_write_b32 v100, v198 offset:14336
	v_add_f32_dpp v196, v196, v196 row_half_mirror row_mask:0xf bank_mask:0xf bound_ctrl:1
	s_nop 1
	v_add_f32_dpp v196, v196, v196 row_mirror row_mask:0xf bank_mask:0xf bound_ctrl:1
	v_mov_b32_e32 v197, v196
	s_nop 1
	v_permlane16_swap_b32_e32 v196, v197
	v_add_f32_e32 v196, v196, v197
	v_pk_fma_f32 v[82:83], v[196:197], v[168:169], v[194:195] op_sel_hi:[0,1,1] neg_lo:[1,0,0] neg_hi:[1,0,0]
	ds_read2st64_b64 v[162:165], v153 offset0:60 offset1:44
	ds_read2st64_b64 v[166:169], v153 offset0:28 offset1:76
	ds_read_b32 v170, v99 offset:1600
	ds_read_b64 v[188:189], v98 offset:6656
	s_waitcnt lgkmcnt(5)
	v_pk_mul_f32 v[190:191], v[82:83], v[174:175]
	v_add_f32_e32 v196, v190, v191
	v_pk_mul_f32 v[192:193], v[82:83], v[186:187]
	v_pk_mul_f32 v[194:195], v[82:83], v[176:177]
	v_add_f32_dpp v196, v196, v196 quad_perm:[1,0,3,2] row_mask:0xf bank_mask:0xf bound_ctrl:1
	v_add_f32_e32 v198, v192, v193
	v_pk_fma_f32 v[194:195], v[182:183], v[178:179], v[194:195] op_sel_hi:[0,1,1]
	v_add_f32_dpp v196, v196, v196 quad_perm:[2,3,0,1] row_mask:0xf bank_mask:0xf bound_ctrl:1
	v_add_f32_dpp v198, v198, v198 quad_perm:[1,0,3,2] row_mask:0xf bank_mask:0xf bound_ctrl:1
	ds_write_b32 v100, v198 offset:13824
	v_add_f32_dpp v196, v196, v196 row_half_mirror row_mask:0xf bank_mask:0xf bound_ctrl:1
	s_nop 1
	v_add_f32_dpp v196, v196, v196 row_mirror row_mask:0xf bank_mask:0xf bound_ctrl:1
	v_mov_b32_e32 v197, v196
	s_nop 1
	v_permlane16_swap_b32_e32 v196, v197
	v_add_f32_e32 v196, v196, v197
	v_pk_fma_f32 v[82:83], v[196:197], v[180:181], v[194:195] op_sel_hi:[0,1,1] neg_lo:[1,0,0] neg_hi:[1,0,0]
	ds_read2st64_b64 v[174:177], v98 offset0:60 offset1:44
	ds_read2st64_b64 v[178:181], v98 offset0:28 offset1:76
	ds_read_b32 v182, v99 offset:1536
	ds_read_b64 v[186:187], v98 offset:6400
	s_waitcnt lgkmcnt(5)
	v_pk_mul_f32 v[190:191], v[82:83], v[162:163]
	v_add_f32_e32 v196, v190, v191
	v_pk_mul_f32 v[192:193], v[82:83], v[188:189]
	v_pk_mul_f32 v[194:195], v[82:83], v[164:165]
	v_add_f32_dpp v196, v196, v196 quad_perm:[1,0,3,2] row_mask:0xf bank_mask:0xf bound_ctrl:1
	v_add_f32_e32 v198, v192, v193
	v_pk_fma_f32 v[194:195], v[170:171], v[166:167], v[194:195] op_sel_hi:[0,1,1]
	v_add_f32_dpp v196, v196, v196 quad_perm:[2,3,0,1] row_mask:0xf bank_mask:0xf bound_ctrl:1
	v_add_f32_dpp v198, v198, v198 quad_perm:[1,0,3,2] row_mask:0xf bank_mask:0xf bound_ctrl:1
	ds_write_b32 v100, v198 offset:13312
	v_add_f32_dpp v196, v196, v196 row_half_mirror row_mask:0xf bank_mask:0xf bound_ctrl:1
	s_nop 1
	v_add_f32_dpp v196, v196, v196 row_mirror row_mask:0xf bank_mask:0xf bound_ctrl:1
	v_mov_b32_e32 v197, v196
	s_nop 1
	v_permlane16_swap_b32_e32 v196, v197
	v_add_f32_e32 v196, v196, v197
	v_pk_fma_f32 v[82:83], v[196:197], v[168:169], v[194:195] op_sel_hi:[0,1,1] neg_lo:[1,0,0] neg_hi:[1,0,0]
	ds_read2st64_b64 v[162:165], v153 offset0:59 offset1:43
	ds_read2st64_b64 v[166:169], v153 offset0:27 offset1:75
	ds_read_b32 v170, v99 offset:1472
	ds_read_b64 v[188:189], v98 offset:6144
	s_waitcnt lgkmcnt(5)
	v_pk_mul_f32 v[190:191], v[82:83], v[174:175]
	v_add_f32_e32 v196, v190, v191
	v_pk_mul_f32 v[192:193], v[82:83], v[186:187]
	v_pk_mul_f32 v[194:195], v[82:83], v[176:177]
	v_add_f32_dpp v196, v196, v196 quad_perm:[1,0,3,2] row_mask:0xf bank_mask:0xf bound_ctrl:1
	v_add_f32_e32 v198, v192, v193
	v_pk_fma_f32 v[194:195], v[182:183], v[178:179], v[194:195] op_sel_hi:[0,1,1]
	v_add_f32_dpp v196, v196, v196 quad_perm:[2,3,0,1] row_mask:0xf bank_mask:0xf bound_ctrl:1
	v_add_f32_dpp v198, v198, v198 quad_perm:[1,0,3,2] row_mask:0xf bank_mask:0xf bound_ctrl:1
	ds_write_b32 v100, v198 offset:12800
	v_add_f32_dpp v196, v196, v196 row_half_mirror row_mask:0xf bank_mask:0xf bound_ctrl:1
	s_nop 1
	v_add_f32_dpp v196, v196, v196 row_mirror row_mask:0xf bank_mask:0xf bound_ctrl:1
	v_mov_b32_e32 v197, v196
	s_nop 1
	v_permlane16_swap_b32_e32 v196, v197
	v_add_f32_e32 v196, v196, v197
	v_pk_fma_f32 v[82:83], v[196:197], v[180:181], v[194:195] op_sel_hi:[0,1,1] neg_lo:[1,0,0] neg_hi:[1,0,0]
	ds_read2st64_b64 v[174:177], v98 offset0:59 offset1:43
	ds_read2st64_b64 v[178:181], v98 offset0:27 offset1:75
	ds_read_b32 v182, v99 offset:1408
	ds_read_b64 v[186:187], v98 offset:5888
	s_waitcnt lgkmcnt(5)
	v_pk_mul_f32 v[190:191], v[82:83], v[162:163]
	v_add_f32_e32 v196, v190, v191
	v_pk_mul_f32 v[192:193], v[82:83], v[188:189]
	v_pk_mul_f32 v[194:195], v[82:83], v[164:165]
	v_add_f32_dpp v196, v196, v196 quad_perm:[1,0,3,2] row_mask:0xf bank_mask:0xf bound_ctrl:1
	v_add_f32_e32 v198, v192, v193
	v_pk_fma_f32 v[194:195], v[170:171], v[166:167], v[194:195] op_sel_hi:[0,1,1]
	v_add_f32_dpp v196, v196, v196 quad_perm:[2,3,0,1] row_mask:0xf bank_mask:0xf bound_ctrl:1
	v_add_f32_dpp v198, v198, v198 quad_perm:[1,0,3,2] row_mask:0xf bank_mask:0xf bound_ctrl:1
	ds_write_b32 v100, v198 offset:12288
	v_add_f32_dpp v196, v196, v196 row_half_mirror row_mask:0xf bank_mask:0xf bound_ctrl:1
	s_nop 1
	v_add_f32_dpp v196, v196, v196 row_mirror row_mask:0xf bank_mask:0xf bound_ctrl:1
	v_mov_b32_e32 v197, v196
	s_nop 1
	v_permlane16_swap_b32_e32 v196, v197
	v_add_f32_e32 v196, v196, v197
	v_pk_fma_f32 v[82:83], v[196:197], v[168:169], v[194:195] op_sel_hi:[0,1,1] neg_lo:[1,0,0] neg_hi:[1,0,0]
	ds_read2st64_b64 v[162:165], v153 offset0:58 offset1:42
	ds_read2st64_b64 v[166:169], v153 offset0:26 offset1:74
	ds_read_b32 v170, v99 offset:1344
	ds_read_b64 v[188:189], v98 offset:5632
	s_waitcnt lgkmcnt(5)
	v_pk_mul_f32 v[190:191], v[82:83], v[174:175]
	v_add_f32_e32 v196, v190, v191
	v_pk_mul_f32 v[192:193], v[82:83], v[186:187]
	v_pk_mul_f32 v[194:195], v[82:83], v[176:177]
	v_add_f32_dpp v196, v196, v196 quad_perm:[1,0,3,2] row_mask:0xf bank_mask:0xf bound_ctrl:1
	v_add_f32_e32 v198, v192, v193
	v_pk_fma_f32 v[194:195], v[182:183], v[178:179], v[194:195] op_sel_hi:[0,1,1]
	v_add_f32_dpp v196, v196, v196 quad_perm:[2,3,0,1] row_mask:0xf bank_mask:0xf bound_ctrl:1
	v_add_f32_dpp v198, v198, v198 quad_perm:[1,0,3,2] row_mask:0xf bank_mask:0xf bound_ctrl:1
	ds_write_b32 v100, v198 offset:11776
	v_add_f32_dpp v196, v196, v196 row_half_mirror row_mask:0xf bank_mask:0xf bound_ctrl:1
	s_nop 1
	v_add_f32_dpp v196, v196, v196 row_mirror row_mask:0xf bank_mask:0xf bound_ctrl:1
	v_mov_b32_e32 v197, v196
	s_nop 1
	v_permlane16_swap_b32_e32 v196, v197
	v_add_f32_e32 v196, v196, v197
	v_pk_fma_f32 v[82:83], v[196:197], v[180:181], v[194:195] op_sel_hi:[0,1,1] neg_lo:[1,0,0] neg_hi:[1,0,0]
	ds_read2st64_b64 v[174:177], v98 offset0:58 offset1:42
	ds_read2st64_b64 v[178:181], v98 offset0:26 offset1:74
	ds_read_b32 v182, v99 offset:1280
	ds_read_b64 v[186:187], v98 offset:5376
	s_waitcnt lgkmcnt(5)
	v_pk_mul_f32 v[190:191], v[82:83], v[162:163]
	v_add_f32_e32 v196, v190, v191
	v_pk_mul_f32 v[192:193], v[82:83], v[188:189]
	v_pk_mul_f32 v[194:195], v[82:83], v[164:165]
	v_add_f32_dpp v196, v196, v196 quad_perm:[1,0,3,2] row_mask:0xf bank_mask:0xf bound_ctrl:1
	v_add_f32_e32 v198, v192, v193
	v_pk_fma_f32 v[194:195], v[170:171], v[166:167], v[194:195] op_sel_hi:[0,1,1]
	v_add_f32_dpp v196, v196, v196 quad_perm:[2,3,0,1] row_mask:0xf bank_mask:0xf bound_ctrl:1
	v_add_f32_dpp v198, v198, v198 quad_perm:[1,0,3,2] row_mask:0xf bank_mask:0xf bound_ctrl:1
	ds_write_b32 v100, v198 offset:11264
	v_add_f32_dpp v196, v196, v196 row_half_mirror row_mask:0xf bank_mask:0xf bound_ctrl:1
	s_nop 1
	v_add_f32_dpp v196, v196, v196 row_mirror row_mask:0xf bank_mask:0xf bound_ctrl:1
	v_mov_b32_e32 v197, v196
	s_nop 1
	v_permlane16_swap_b32_e32 v196, v197
	v_add_f32_e32 v196, v196, v197
	v_pk_fma_f32 v[82:83], v[196:197], v[168:169], v[194:195] op_sel_hi:[0,1,1] neg_lo:[1,0,0] neg_hi:[1,0,0]
	ds_read2st64_b64 v[162:165], v153 offset0:57 offset1:41
	ds_read2st64_b64 v[166:169], v153 offset0:25 offset1:73
	ds_read_b32 v170, v99 offset:1216
	ds_read_b64 v[188:189], v98 offset:5120
	s_waitcnt lgkmcnt(5)
	v_pk_mul_f32 v[190:191], v[82:83], v[174:175]
	v_add_f32_e32 v196, v190, v191
	v_pk_mul_f32 v[192:193], v[82:83], v[186:187]
	v_pk_mul_f32 v[194:195], v[82:83], v[176:177]
	v_add_f32_dpp v196, v196, v196 quad_perm:[1,0,3,2] row_mask:0xf bank_mask:0xf bound_ctrl:1
	v_add_f32_e32 v198, v192, v193
	v_pk_fma_f32 v[194:195], v[182:183], v[178:179], v[194:195] op_sel_hi:[0,1,1]
	v_add_f32_dpp v196, v196, v196 quad_perm:[2,3,0,1] row_mask:0xf bank_mask:0xf bound_ctrl:1
	v_add_f32_dpp v198, v198, v198 quad_perm:[1,0,3,2] row_mask:0xf bank_mask:0xf bound_ctrl:1
	ds_write_b32 v100, v198 offset:10752
	v_add_f32_dpp v196, v196, v196 row_half_mirror row_mask:0xf bank_mask:0xf bound_ctrl:1
	s_nop 1
	v_add_f32_dpp v196, v196, v196 row_mirror row_mask:0xf bank_mask:0xf bound_ctrl:1
	v_mov_b32_e32 v197, v196
	s_nop 1
	v_permlane16_swap_b32_e32 v196, v197
	v_add_f32_e32 v196, v196, v197
	v_pk_fma_f32 v[82:83], v[196:197], v[180:181], v[194:195] op_sel_hi:[0,1,1] neg_lo:[1,0,0] neg_hi:[1,0,0]
	ds_read2st64_b64 v[174:177], v98 offset0:57 offset1:41
	ds_read2st64_b64 v[178:181], v98 offset0:25 offset1:73
	ds_read_b32 v182, v99 offset:1152
	ds_read_b64 v[186:187], v98 offset:4864
	s_waitcnt lgkmcnt(5)
	v_pk_mul_f32 v[190:191], v[82:83], v[162:163]
	v_add_f32_e32 v196, v190, v191
	v_pk_mul_f32 v[192:193], v[82:83], v[188:189]
	v_pk_mul_f32 v[194:195], v[82:83], v[164:165]
	v_add_f32_dpp v196, v196, v196 quad_perm:[1,0,3,2] row_mask:0xf bank_mask:0xf bound_ctrl:1
	v_add_f32_e32 v198, v192, v193
	v_pk_fma_f32 v[194:195], v[170:171], v[166:167], v[194:195] op_sel_hi:[0,1,1]
	v_add_f32_dpp v196, v196, v196 quad_perm:[2,3,0,1] row_mask:0xf bank_mask:0xf bound_ctrl:1
	v_add_f32_dpp v198, v198, v198 quad_perm:[1,0,3,2] row_mask:0xf bank_mask:0xf bound_ctrl:1
	ds_write_b32 v100, v198 offset:10240
	v_add_f32_dpp v196, v196, v196 row_half_mirror row_mask:0xf bank_mask:0xf bound_ctrl:1
	s_nop 1
	v_add_f32_dpp v196, v196, v196 row_mirror row_mask:0xf bank_mask:0xf bound_ctrl:1
	v_mov_b32_e32 v197, v196
	s_nop 1
	v_permlane16_swap_b32_e32 v196, v197
	v_add_f32_e32 v196, v196, v197
	v_pk_fma_f32 v[82:83], v[196:197], v[168:169], v[194:195] op_sel_hi:[0,1,1] neg_lo:[1,0,0] neg_hi:[1,0,0]
	ds_read2st64_b64 v[162:165], v153 offset0:56 offset1:40
	ds_read2st64_b64 v[166:169], v153 offset0:24 offset1:72
	ds_read_b32 v170, v99 offset:1088
	ds_read_b64 v[188:189], v98 offset:4608
	s_waitcnt lgkmcnt(5)
	v_pk_mul_f32 v[190:191], v[82:83], v[174:175]
	v_add_f32_e32 v196, v190, v191
	v_pk_mul_f32 v[192:193], v[82:83], v[186:187]
	v_pk_mul_f32 v[194:195], v[82:83], v[176:177]
	v_add_f32_dpp v196, v196, v196 quad_perm:[1,0,3,2] row_mask:0xf bank_mask:0xf bound_ctrl:1
	v_add_f32_e32 v198, v192, v193
	v_pk_fma_f32 v[194:195], v[182:183], v[178:179], v[194:195] op_sel_hi:[0,1,1]
	v_add_f32_dpp v196, v196, v196 quad_perm:[2,3,0,1] row_mask:0xf bank_mask:0xf bound_ctrl:1
	v_add_f32_dpp v198, v198, v198 quad_perm:[1,0,3,2] row_mask:0xf bank_mask:0xf bound_ctrl:1
	ds_write_b32 v100, v198 offset:9728
	v_add_f32_dpp v196, v196, v196 row_half_mirror row_mask:0xf bank_mask:0xf bound_ctrl:1
	s_nop 1
	v_add_f32_dpp v196, v196, v196 row_mirror row_mask:0xf bank_mask:0xf bound_ctrl:1
	v_mov_b32_e32 v197, v196
	s_nop 1
	v_permlane16_swap_b32_e32 v196, v197
	v_add_f32_e32 v196, v196, v197
	v_pk_fma_f32 v[82:83], v[196:197], v[180:181], v[194:195] op_sel_hi:[0,1,1] neg_lo:[1,0,0] neg_hi:[1,0,0]
	ds_read2st64_b64 v[174:177], v98 offset0:56 offset1:40
	ds_read2st64_b64 v[178:181], v98 offset0:24 offset1:72
	ds_read_b32 v182, v99 offset:1024
	ds_read_b64 v[186:187], v98 offset:4352
	s_waitcnt lgkmcnt(5)
	v_pk_mul_f32 v[190:191], v[82:83], v[162:163]
	v_add_f32_e32 v196, v190, v191
	v_pk_mul_f32 v[192:193], v[82:83], v[188:189]
	v_pk_mul_f32 v[194:195], v[82:83], v[164:165]
	v_add_f32_dpp v196, v196, v196 quad_perm:[1,0,3,2] row_mask:0xf bank_mask:0xf bound_ctrl:1
	v_add_f32_e32 v198, v192, v193
	v_pk_fma_f32 v[194:195], v[170:171], v[166:167], v[194:195] op_sel_hi:[0,1,1]
	v_add_f32_dpp v196, v196, v196 quad_perm:[2,3,0,1] row_mask:0xf bank_mask:0xf bound_ctrl:1
	v_add_f32_dpp v198, v198, v198 quad_perm:[1,0,3,2] row_mask:0xf bank_mask:0xf bound_ctrl:1
	ds_write_b32 v100, v198 offset:9216
	v_add_f32_dpp v196, v196, v196 row_half_mirror row_mask:0xf bank_mask:0xf bound_ctrl:1
	s_nop 1
	v_add_f32_dpp v196, v196, v196 row_mirror row_mask:0xf bank_mask:0xf bound_ctrl:1
	v_mov_b32_e32 v197, v196
	s_nop 1
	v_permlane16_swap_b32_e32 v196, v197
	v_add_f32_e32 v196, v196, v197
	v_pk_fma_f32 v[82:83], v[196:197], v[168:169], v[194:195] op_sel_hi:[0,1,1] neg_lo:[1,0,0] neg_hi:[1,0,0]
	ds_read2st64_b64 v[162:165], v153 offset0:55 offset1:39
	ds_read2st64_b64 v[166:169], v153 offset0:23 offset1:71
	ds_read_b32 v170, v99 offset:960
	ds_read_b64 v[188:189], v98 offset:4096
	s_waitcnt lgkmcnt(5)
	v_pk_mul_f32 v[190:191], v[82:83], v[174:175]
	v_add_f32_e32 v196, v190, v191
	v_pk_mul_f32 v[192:193], v[82:83], v[186:187]
	v_pk_mul_f32 v[194:195], v[82:83], v[176:177]
	v_add_f32_dpp v196, v196, v196 quad_perm:[1,0,3,2] row_mask:0xf bank_mask:0xf bound_ctrl:1
	v_add_f32_e32 v198, v192, v193
	v_pk_fma_f32 v[194:195], v[182:183], v[178:179], v[194:195] op_sel_hi:[0,1,1]
	v_add_f32_dpp v196, v196, v196 quad_perm:[2,3,0,1] row_mask:0xf bank_mask:0xf bound_ctrl:1
	v_add_f32_dpp v198, v198, v198 quad_perm:[1,0,3,2] row_mask:0xf bank_mask:0xf bound_ctrl:1
	ds_write_b32 v100, v198 offset:8704
	v_add_f32_dpp v196, v196, v196 row_half_mirror row_mask:0xf bank_mask:0xf bound_ctrl:1
	s_nop 1
	v_add_f32_dpp v196, v196, v196 row_mirror row_mask:0xf bank_mask:0xf bound_ctrl:1
	v_mov_b32_e32 v197, v196
	s_nop 1
	v_permlane16_swap_b32_e32 v196, v197
	v_add_f32_e32 v196, v196, v197
	v_pk_fma_f32 v[82:83], v[196:197], v[180:181], v[194:195] op_sel_hi:[0,1,1] neg_lo:[1,0,0] neg_hi:[1,0,0]
	ds_read2st64_b64 v[174:177], v98 offset0:55 offset1:39
	ds_read2st64_b64 v[178:181], v98 offset0:23 offset1:71
	ds_read_b32 v182, v99 offset:896
	ds_read_b64 v[186:187], v98 offset:3840
	s_waitcnt lgkmcnt(5)
	v_pk_mul_f32 v[190:191], v[82:83], v[162:163]
	v_add_f32_e32 v196, v190, v191
	v_pk_mul_f32 v[192:193], v[82:83], v[188:189]
	v_pk_mul_f32 v[194:195], v[82:83], v[164:165]
	v_add_f32_dpp v196, v196, v196 quad_perm:[1,0,3,2] row_mask:0xf bank_mask:0xf bound_ctrl:1
	v_add_f32_e32 v198, v192, v193
	v_pk_fma_f32 v[194:195], v[170:171], v[166:167], v[194:195] op_sel_hi:[0,1,1]
	v_add_f32_dpp v196, v196, v196 quad_perm:[2,3,0,1] row_mask:0xf bank_mask:0xf bound_ctrl:1
	v_add_f32_dpp v198, v198, v198 quad_perm:[1,0,3,2] row_mask:0xf bank_mask:0xf bound_ctrl:1
	ds_write_b32 v100, v198 offset:8192
	v_add_f32_dpp v196, v196, v196 row_half_mirror row_mask:0xf bank_mask:0xf bound_ctrl:1
	s_nop 1
	v_add_f32_dpp v196, v196, v196 row_mirror row_mask:0xf bank_mask:0xf bound_ctrl:1
	v_mov_b32_e32 v197, v196
	s_nop 1
	v_permlane16_swap_b32_e32 v196, v197
	v_add_f32_e32 v196, v196, v197
	v_pk_fma_f32 v[82:83], v[196:197], v[168:169], v[194:195] op_sel_hi:[0,1,1] neg_lo:[1,0,0] neg_hi:[1,0,0]
	ds_read2st64_b64 v[162:165], v153 offset0:54 offset1:38
	ds_read2st64_b64 v[166:169], v153 offset0:22 offset1:70
	ds_read_b32 v170, v99 offset:832
	ds_read_b64 v[188:189], v98 offset:3584
	s_waitcnt lgkmcnt(5)
	v_pk_mul_f32 v[190:191], v[82:83], v[174:175]
	v_add_f32_e32 v196, v190, v191
	v_pk_mul_f32 v[192:193], v[82:83], v[186:187]
	v_pk_mul_f32 v[194:195], v[82:83], v[176:177]
	v_add_f32_dpp v196, v196, v196 quad_perm:[1,0,3,2] row_mask:0xf bank_mask:0xf bound_ctrl:1
	v_add_f32_e32 v198, v192, v193
	v_pk_fma_f32 v[194:195], v[182:183], v[178:179], v[194:195] op_sel_hi:[0,1,1]
	v_add_f32_dpp v196, v196, v196 quad_perm:[2,3,0,1] row_mask:0xf bank_mask:0xf bound_ctrl:1
	v_add_f32_dpp v198, v198, v198 quad_perm:[1,0,3,2] row_mask:0xf bank_mask:0xf bound_ctrl:1
	ds_write_b32 v100, v198 offset:7680
	v_add_f32_dpp v196, v196, v196 row_half_mirror row_mask:0xf bank_mask:0xf bound_ctrl:1
	s_nop 1
	v_add_f32_dpp v196, v196, v196 row_mirror row_mask:0xf bank_mask:0xf bound_ctrl:1
	v_mov_b32_e32 v197, v196
	s_nop 1
	v_permlane16_swap_b32_e32 v196, v197
	v_add_f32_e32 v196, v196, v197
	v_pk_fma_f32 v[82:83], v[196:197], v[180:181], v[194:195] op_sel_hi:[0,1,1] neg_lo:[1,0,0] neg_hi:[1,0,0]
	ds_read2st64_b64 v[174:177], v98 offset0:54 offset1:38
	ds_read2st64_b64 v[178:181], v98 offset0:22 offset1:70
	ds_read_b32 v182, v99 offset:768
	ds_read_b64 v[186:187], v98 offset:3328
	s_waitcnt lgkmcnt(5)
	v_pk_mul_f32 v[190:191], v[82:83], v[162:163]
	v_add_f32_e32 v196, v190, v191
	v_pk_mul_f32 v[192:193], v[82:83], v[188:189]
	v_pk_mul_f32 v[194:195], v[82:83], v[164:165]
	v_add_f32_dpp v196, v196, v196 quad_perm:[1,0,3,2] row_mask:0xf bank_mask:0xf bound_ctrl:1
	v_add_f32_e32 v198, v192, v193
	v_pk_fma_f32 v[194:195], v[170:171], v[166:167], v[194:195] op_sel_hi:[0,1,1]
	v_add_f32_dpp v196, v196, v196 quad_perm:[2,3,0,1] row_mask:0xf bank_mask:0xf bound_ctrl:1
	v_add_f32_dpp v198, v198, v198 quad_perm:[1,0,3,2] row_mask:0xf bank_mask:0xf bound_ctrl:1
	ds_write_b32 v100, v198 offset:7168
	v_add_f32_dpp v196, v196, v196 row_half_mirror row_mask:0xf bank_mask:0xf bound_ctrl:1
	s_nop 1
	v_add_f32_dpp v196, v196, v196 row_mirror row_mask:0xf bank_mask:0xf bound_ctrl:1
	v_mov_b32_e32 v197, v196
	s_nop 1
	v_permlane16_swap_b32_e32 v196, v197
	v_add_f32_e32 v196, v196, v197
	v_pk_fma_f32 v[82:83], v[196:197], v[168:169], v[194:195] op_sel_hi:[0,1,1] neg_lo:[1,0,0] neg_hi:[1,0,0]
	ds_read2st64_b64 v[162:165], v153 offset0:53 offset1:37
	ds_read2st64_b64 v[166:169], v153 offset0:21 offset1:69
	ds_read_b32 v170, v99 offset:704
	ds_read_b64 v[188:189], v98 offset:3072
	s_waitcnt lgkmcnt(5)
	v_pk_mul_f32 v[190:191], v[82:83], v[174:175]
	v_add_f32_e32 v196, v190, v191
	v_pk_mul_f32 v[192:193], v[82:83], v[186:187]
	v_pk_mul_f32 v[194:195], v[82:83], v[176:177]
	v_add_f32_dpp v196, v196, v196 quad_perm:[1,0,3,2] row_mask:0xf bank_mask:0xf bound_ctrl:1
	v_add_f32_e32 v198, v192, v193
	v_pk_fma_f32 v[194:195], v[182:183], v[178:179], v[194:195] op_sel_hi:[0,1,1]
	v_add_f32_dpp v196, v196, v196 quad_perm:[2,3,0,1] row_mask:0xf bank_mask:0xf bound_ctrl:1
	v_add_f32_dpp v198, v198, v198 quad_perm:[1,0,3,2] row_mask:0xf bank_mask:0xf bound_ctrl:1
	ds_write_b32 v100, v198 offset:6656
	v_add_f32_dpp v196, v196, v196 row_half_mirror row_mask:0xf bank_mask:0xf bound_ctrl:1
	s_nop 1
	v_add_f32_dpp v196, v196, v196 row_mirror row_mask:0xf bank_mask:0xf bound_ctrl:1
	v_mov_b32_e32 v197, v196
	s_nop 1
	v_permlane16_swap_b32_e32 v196, v197
	v_add_f32_e32 v196, v196, v197
	v_pk_fma_f32 v[82:83], v[196:197], v[180:181], v[194:195] op_sel_hi:[0,1,1] neg_lo:[1,0,0] neg_hi:[1,0,0]
	ds_read2st64_b64 v[174:177], v98 offset0:53 offset1:37
	ds_read2st64_b64 v[178:181], v98 offset0:21 offset1:69
	ds_read_b32 v182, v99 offset:640
	ds_read_b64 v[186:187], v98 offset:2816
	s_waitcnt lgkmcnt(5)
	v_pk_mul_f32 v[190:191], v[82:83], v[162:163]
	v_add_f32_e32 v196, v190, v191
	v_pk_mul_f32 v[192:193], v[82:83], v[188:189]
	v_pk_mul_f32 v[194:195], v[82:83], v[164:165]
	v_add_f32_dpp v196, v196, v196 quad_perm:[1,0,3,2] row_mask:0xf bank_mask:0xf bound_ctrl:1
	v_add_f32_e32 v198, v192, v193
	v_pk_fma_f32 v[194:195], v[170:171], v[166:167], v[194:195] op_sel_hi:[0,1,1]
	v_add_f32_dpp v196, v196, v196 quad_perm:[2,3,0,1] row_mask:0xf bank_mask:0xf bound_ctrl:1
	v_add_f32_dpp v198, v198, v198 quad_perm:[1,0,3,2] row_mask:0xf bank_mask:0xf bound_ctrl:1
	ds_write_b32 v100, v198 offset:6144
	v_add_f32_dpp v196, v196, v196 row_half_mirror row_mask:0xf bank_mask:0xf bound_ctrl:1
	s_nop 1
	v_add_f32_dpp v196, v196, v196 row_mirror row_mask:0xf bank_mask:0xf bound_ctrl:1
	v_mov_b32_e32 v197, v196
	s_nop 1
	v_permlane16_swap_b32_e32 v196, v197
	v_add_f32_e32 v196, v196, v197
	v_pk_fma_f32 v[82:83], v[196:197], v[168:169], v[194:195] op_sel_hi:[0,1,1] neg_lo:[1,0,0] neg_hi:[1,0,0]
	ds_read2st64_b64 v[162:165], v153 offset0:52 offset1:36
	ds_read2st64_b64 v[166:169], v153 offset0:20 offset1:68
	ds_read_b32 v170, v99 offset:576
	ds_read_b64 v[188:189], v98 offset:2560
	s_waitcnt lgkmcnt(5)
	v_pk_mul_f32 v[190:191], v[82:83], v[174:175]
	v_add_f32_e32 v196, v190, v191
	v_pk_mul_f32 v[192:193], v[82:83], v[186:187]
	v_pk_mul_f32 v[194:195], v[82:83], v[176:177]
	v_add_f32_dpp v196, v196, v196 quad_perm:[1,0,3,2] row_mask:0xf bank_mask:0xf bound_ctrl:1
	v_add_f32_e32 v198, v192, v193
	v_pk_fma_f32 v[194:195], v[182:183], v[178:179], v[194:195] op_sel_hi:[0,1,1]
	v_add_f32_dpp v196, v196, v196 quad_perm:[2,3,0,1] row_mask:0xf bank_mask:0xf bound_ctrl:1
	v_add_f32_dpp v198, v198, v198 quad_perm:[1,0,3,2] row_mask:0xf bank_mask:0xf bound_ctrl:1
	ds_write_b32 v100, v198 offset:5632
	v_add_f32_dpp v196, v196, v196 row_half_mirror row_mask:0xf bank_mask:0xf bound_ctrl:1
	s_nop 1
	v_add_f32_dpp v196, v196, v196 row_mirror row_mask:0xf bank_mask:0xf bound_ctrl:1
	v_mov_b32_e32 v197, v196
	s_nop 1
	v_permlane16_swap_b32_e32 v196, v197
	v_add_f32_e32 v196, v196, v197
	v_pk_fma_f32 v[82:83], v[196:197], v[180:181], v[194:195] op_sel_hi:[0,1,1] neg_lo:[1,0,0] neg_hi:[1,0,0]
	ds_read2st64_b64 v[174:177], v98 offset0:52 offset1:36
	ds_read2st64_b64 v[178:181], v98 offset0:20 offset1:68
	ds_read_b32 v182, v99 offset:512
	ds_read_b64 v[186:187], v98 offset:2304
	s_waitcnt lgkmcnt(5)
	v_pk_mul_f32 v[190:191], v[82:83], v[162:163]
	v_add_f32_e32 v196, v190, v191
	v_pk_mul_f32 v[192:193], v[82:83], v[188:189]
	v_pk_mul_f32 v[194:195], v[82:83], v[164:165]
	v_add_f32_dpp v196, v196, v196 quad_perm:[1,0,3,2] row_mask:0xf bank_mask:0xf bound_ctrl:1
	v_add_f32_e32 v198, v192, v193
	v_pk_fma_f32 v[194:195], v[170:171], v[166:167], v[194:195] op_sel_hi:[0,1,1]
	v_add_f32_dpp v196, v196, v196 quad_perm:[2,3,0,1] row_mask:0xf bank_mask:0xf bound_ctrl:1
	v_add_f32_dpp v198, v198, v198 quad_perm:[1,0,3,2] row_mask:0xf bank_mask:0xf bound_ctrl:1
	ds_write_b32 v100, v198 offset:5120
	v_add_f32_dpp v196, v196, v196 row_half_mirror row_mask:0xf bank_mask:0xf bound_ctrl:1
	s_nop 1
	v_add_f32_dpp v196, v196, v196 row_mirror row_mask:0xf bank_mask:0xf bound_ctrl:1
	v_mov_b32_e32 v197, v196
	s_nop 1
	v_permlane16_swap_b32_e32 v196, v197
	v_add_f32_e32 v196, v196, v197
	v_pk_fma_f32 v[82:83], v[196:197], v[168:169], v[194:195] op_sel_hi:[0,1,1] neg_lo:[1,0,0] neg_hi:[1,0,0]
	ds_read2st64_b64 v[162:165], v153 offset0:51 offset1:35
	ds_read2st64_b64 v[166:169], v153 offset0:19 offset1:67
	ds_read_b32 v170, v99 offset:448
	ds_read_b64 v[188:189], v98 offset:2048
	s_waitcnt lgkmcnt(5)
	v_pk_mul_f32 v[190:191], v[82:83], v[174:175]
	v_add_f32_e32 v196, v190, v191
	v_pk_mul_f32 v[192:193], v[82:83], v[186:187]
	v_pk_mul_f32 v[194:195], v[82:83], v[176:177]
	v_add_f32_dpp v196, v196, v196 quad_perm:[1,0,3,2] row_mask:0xf bank_mask:0xf bound_ctrl:1
	v_add_f32_e32 v198, v192, v193
	v_pk_fma_f32 v[194:195], v[182:183], v[178:179], v[194:195] op_sel_hi:[0,1,1]
	v_add_f32_dpp v196, v196, v196 quad_perm:[2,3,0,1] row_mask:0xf bank_mask:0xf bound_ctrl:1
	v_add_f32_dpp v198, v198, v198 quad_perm:[1,0,3,2] row_mask:0xf bank_mask:0xf bound_ctrl:1
	ds_write_b32 v100, v198 offset:4608
	v_add_f32_dpp v196, v196, v196 row_half_mirror row_mask:0xf bank_mask:0xf bound_ctrl:1
	s_nop 1
	v_add_f32_dpp v196, v196, v196 row_mirror row_mask:0xf bank_mask:0xf bound_ctrl:1
	v_mov_b32_e32 v197, v196
	s_nop 1
	v_permlane16_swap_b32_e32 v196, v197
	v_add_f32_e32 v196, v196, v197
	v_pk_fma_f32 v[82:83], v[196:197], v[180:181], v[194:195] op_sel_hi:[0,1,1] neg_lo:[1,0,0] neg_hi:[1,0,0]
	ds_read2st64_b64 v[174:177], v98 offset0:51 offset1:35
	ds_read2st64_b64 v[178:181], v98 offset0:19 offset1:67
	ds_read_b32 v182, v99 offset:384
	ds_read_b64 v[186:187], v98 offset:1792
	s_waitcnt lgkmcnt(5)
	v_pk_mul_f32 v[190:191], v[82:83], v[162:163]
	v_add_f32_e32 v196, v190, v191
	v_pk_mul_f32 v[192:193], v[82:83], v[188:189]
	v_pk_mul_f32 v[194:195], v[82:83], v[164:165]
	v_add_f32_dpp v196, v196, v196 quad_perm:[1,0,3,2] row_mask:0xf bank_mask:0xf bound_ctrl:1
	v_add_f32_e32 v198, v192, v193
	v_pk_fma_f32 v[194:195], v[170:171], v[166:167], v[194:195] op_sel_hi:[0,1,1]
	v_add_f32_dpp v196, v196, v196 quad_perm:[2,3,0,1] row_mask:0xf bank_mask:0xf bound_ctrl:1
	v_add_f32_dpp v198, v198, v198 quad_perm:[1,0,3,2] row_mask:0xf bank_mask:0xf bound_ctrl:1
	ds_write_b32 v100, v198 offset:4096
	v_add_f32_dpp v196, v196, v196 row_half_mirror row_mask:0xf bank_mask:0xf bound_ctrl:1
	s_nop 1
	v_add_f32_dpp v196, v196, v196 row_mirror row_mask:0xf bank_mask:0xf bound_ctrl:1
	v_mov_b32_e32 v197, v196
	s_nop 1
	v_permlane16_swap_b32_e32 v196, v197
	v_add_f32_e32 v196, v196, v197
	v_pk_fma_f32 v[82:83], v[196:197], v[168:169], v[194:195] op_sel_hi:[0,1,1] neg_lo:[1,0,0] neg_hi:[1,0,0]
	ds_read2st64_b64 v[162:165], v153 offset0:50 offset1:34
	ds_read2st64_b64 v[166:169], v153 offset0:18 offset1:66
	ds_read_b32 v170, v99 offset:320
	ds_read_b64 v[188:189], v98 offset:1536
	s_waitcnt lgkmcnt(5)
	v_pk_mul_f32 v[190:191], v[82:83], v[174:175]
	v_add_f32_e32 v196, v190, v191
	v_pk_mul_f32 v[192:193], v[82:83], v[186:187]
	v_pk_mul_f32 v[194:195], v[82:83], v[176:177]
	v_add_f32_dpp v196, v196, v196 quad_perm:[1,0,3,2] row_mask:0xf bank_mask:0xf bound_ctrl:1
	v_add_f32_e32 v198, v192, v193
	v_pk_fma_f32 v[194:195], v[182:183], v[178:179], v[194:195] op_sel_hi:[0,1,1]
	v_add_f32_dpp v196, v196, v196 quad_perm:[2,3,0,1] row_mask:0xf bank_mask:0xf bound_ctrl:1
	v_add_f32_dpp v198, v198, v198 quad_perm:[1,0,3,2] row_mask:0xf bank_mask:0xf bound_ctrl:1
	ds_write_b32 v100, v198 offset:3584
	v_add_f32_dpp v196, v196, v196 row_half_mirror row_mask:0xf bank_mask:0xf bound_ctrl:1
	s_nop 1
	v_add_f32_dpp v196, v196, v196 row_mirror row_mask:0xf bank_mask:0xf bound_ctrl:1
	v_mov_b32_e32 v197, v196
	s_nop 1
	v_permlane16_swap_b32_e32 v196, v197
	v_add_f32_e32 v196, v196, v197
	v_pk_fma_f32 v[82:83], v[196:197], v[180:181], v[194:195] op_sel_hi:[0,1,1] neg_lo:[1,0,0] neg_hi:[1,0,0]
	ds_read2st64_b64 v[174:177], v98 offset0:50 offset1:34
	ds_read2st64_b64 v[178:181], v98 offset0:18 offset1:66
	ds_read_b32 v182, v99 offset:256
	ds_read_b64 v[186:187], v98 offset:1280
	s_waitcnt lgkmcnt(5)
	v_pk_mul_f32 v[190:191], v[82:83], v[162:163]
	v_add_f32_e32 v196, v190, v191
	v_pk_mul_f32 v[192:193], v[82:83], v[188:189]
	v_pk_mul_f32 v[194:195], v[82:83], v[164:165]
	v_add_f32_dpp v196, v196, v196 quad_perm:[1,0,3,2] row_mask:0xf bank_mask:0xf bound_ctrl:1
	v_add_f32_e32 v198, v192, v193
	v_pk_fma_f32 v[194:195], v[170:171], v[166:167], v[194:195] op_sel_hi:[0,1,1]
	v_add_f32_dpp v196, v196, v196 quad_perm:[2,3,0,1] row_mask:0xf bank_mask:0xf bound_ctrl:1
	v_add_f32_dpp v198, v198, v198 quad_perm:[1,0,3,2] row_mask:0xf bank_mask:0xf bound_ctrl:1
	ds_write_b32 v100, v198 offset:3072
	v_add_f32_dpp v196, v196, v196 row_half_mirror row_mask:0xf bank_mask:0xf bound_ctrl:1
	s_nop 1
	v_add_f32_dpp v196, v196, v196 row_mirror row_mask:0xf bank_mask:0xf bound_ctrl:1
	v_mov_b32_e32 v197, v196
	s_nop 1
	v_permlane16_swap_b32_e32 v196, v197
	v_add_f32_e32 v196, v196, v197
	v_pk_fma_f32 v[82:83], v[196:197], v[168:169], v[194:195] op_sel_hi:[0,1,1] neg_lo:[1,0,0] neg_hi:[1,0,0]
	ds_read2st64_b64 v[162:165], v153 offset0:49 offset1:33
	ds_read2st64_b64 v[166:169], v153 offset0:17 offset1:65
	ds_read_b32 v170, v99 offset:192
	ds_read_b64 v[188:189], v98 offset:1024
	s_waitcnt lgkmcnt(5)
	v_pk_mul_f32 v[190:191], v[82:83], v[174:175]
	v_add_f32_e32 v196, v190, v191
	v_pk_mul_f32 v[192:193], v[82:83], v[186:187]
	v_pk_mul_f32 v[194:195], v[82:83], v[176:177]
	v_add_f32_dpp v196, v196, v196 quad_perm:[1,0,3,2] row_mask:0xf bank_mask:0xf bound_ctrl:1
	v_add_f32_e32 v198, v192, v193
	v_pk_fma_f32 v[194:195], v[182:183], v[178:179], v[194:195] op_sel_hi:[0,1,1]
	v_add_f32_dpp v196, v196, v196 quad_perm:[2,3,0,1] row_mask:0xf bank_mask:0xf bound_ctrl:1
	v_add_f32_dpp v198, v198, v198 quad_perm:[1,0,3,2] row_mask:0xf bank_mask:0xf bound_ctrl:1
	ds_write_b32 v100, v198 offset:2560
	v_add_f32_dpp v196, v196, v196 row_half_mirror row_mask:0xf bank_mask:0xf bound_ctrl:1
	s_nop 1
	v_add_f32_dpp v196, v196, v196 row_mirror row_mask:0xf bank_mask:0xf bound_ctrl:1
	v_mov_b32_e32 v197, v196
	s_nop 1
	v_permlane16_swap_b32_e32 v196, v197
	v_add_f32_e32 v196, v196, v197
	v_pk_fma_f32 v[82:83], v[196:197], v[180:181], v[194:195] op_sel_hi:[0,1,1] neg_lo:[1,0,0] neg_hi:[1,0,0]
	ds_read2st64_b64 v[174:177], v98 offset0:49 offset1:33
	ds_read2st64_b64 v[178:181], v98 offset0:17 offset1:65
	ds_read_b32 v182, v99 offset:128
	ds_read_b64 v[186:187], v98 offset:768
	s_waitcnt lgkmcnt(5)
	v_pk_mul_f32 v[190:191], v[82:83], v[162:163]
	v_add_f32_e32 v196, v190, v191
	v_pk_mul_f32 v[192:193], v[82:83], v[188:189]
	v_pk_mul_f32 v[194:195], v[82:83], v[164:165]
	v_add_f32_dpp v196, v196, v196 quad_perm:[1,0,3,2] row_mask:0xf bank_mask:0xf bound_ctrl:1
	v_add_f32_e32 v198, v192, v193
	v_pk_fma_f32 v[194:195], v[170:171], v[166:167], v[194:195] op_sel_hi:[0,1,1]
	v_add_f32_dpp v196, v196, v196 quad_perm:[2,3,0,1] row_mask:0xf bank_mask:0xf bound_ctrl:1
	v_add_f32_dpp v198, v198, v198 quad_perm:[1,0,3,2] row_mask:0xf bank_mask:0xf bound_ctrl:1
	ds_write_b32 v100, v198 offset:2048
	v_add_f32_dpp v196, v196, v196 row_half_mirror row_mask:0xf bank_mask:0xf bound_ctrl:1
	s_nop 1
	v_add_f32_dpp v196, v196, v196 row_mirror row_mask:0xf bank_mask:0xf bound_ctrl:1
	v_mov_b32_e32 v197, v196
	s_nop 1
	v_permlane16_swap_b32_e32 v196, v197
	v_add_f32_e32 v196, v196, v197
	v_pk_fma_f32 v[82:83], v[196:197], v[168:169], v[194:195] op_sel_hi:[0,1,1] neg_lo:[1,0,0] neg_hi:[1,0,0]
	ds_read2st64_b64 v[162:165], v153 offset0:48 offset1:32
	ds_read2st64_b64 v[166:169], v153 offset0:16 offset1:64
	ds_read_b32 v170, v99 offset:64
	ds_read_b64 v[188:189], v98 offset:512
	s_waitcnt lgkmcnt(5)
	v_pk_mul_f32 v[190:191], v[82:83], v[174:175]
	v_add_f32_e32 v196, v190, v191
	v_pk_mul_f32 v[192:193], v[82:83], v[186:187]
	v_pk_mul_f32 v[194:195], v[82:83], v[176:177]
	v_add_f32_dpp v196, v196, v196 quad_perm:[1,0,3,2] row_mask:0xf bank_mask:0xf bound_ctrl:1
	v_add_f32_e32 v198, v192, v193
	v_pk_fma_f32 v[194:195], v[182:183], v[178:179], v[194:195] op_sel_hi:[0,1,1]
	v_add_f32_dpp v196, v196, v196 quad_perm:[2,3,0,1] row_mask:0xf bank_mask:0xf bound_ctrl:1
	v_add_f32_dpp v198, v198, v198 quad_perm:[1,0,3,2] row_mask:0xf bank_mask:0xf bound_ctrl:1
	ds_write_b32 v100, v198 offset:1536
	v_add_f32_dpp v196, v196, v196 row_half_mirror row_mask:0xf bank_mask:0xf bound_ctrl:1
	s_nop 1
	v_add_f32_dpp v196, v196, v196 row_mirror row_mask:0xf bank_mask:0xf bound_ctrl:1
	v_mov_b32_e32 v197, v196
	s_nop 1
	v_permlane16_swap_b32_e32 v196, v197
	v_add_f32_e32 v196, v196, v197
	v_pk_fma_f32 v[82:83], v[196:197], v[180:181], v[194:195] op_sel_hi:[0,1,1] neg_lo:[1,0,0] neg_hi:[1,0,0]
	ds_read2st64_b64 v[174:177], v98 offset0:48 offset1:32
	ds_read2st64_b64 v[178:181], v98 offset0:16 offset1:64
	ds_read_b32 v182, v99
	ds_read_b64 v[186:187], v98 offset:256
	s_waitcnt lgkmcnt(5)
	v_pk_mul_f32 v[190:191], v[82:83], v[162:163]
	v_add_f32_e32 v196, v190, v191
	v_pk_mul_f32 v[192:193], v[82:83], v[188:189]
	v_pk_mul_f32 v[194:195], v[82:83], v[164:165]
	v_add_f32_dpp v196, v196, v196 quad_perm:[1,0,3,2] row_mask:0xf bank_mask:0xf bound_ctrl:1
	v_add_f32_e32 v198, v192, v193
	v_pk_fma_f32 v[194:195], v[170:171], v[166:167], v[194:195] op_sel_hi:[0,1,1]
	v_add_f32_dpp v196, v196, v196 quad_perm:[2,3,0,1] row_mask:0xf bank_mask:0xf bound_ctrl:1
	v_add_f32_dpp v198, v198, v198 quad_perm:[1,0,3,2] row_mask:0xf bank_mask:0xf bound_ctrl:1
	ds_write_b32 v100, v198 offset:1024
	v_add_f32_dpp v196, v196, v196 row_half_mirror row_mask:0xf bank_mask:0xf bound_ctrl:1
	s_nop 1
	v_add_f32_dpp v196, v196, v196 row_mirror row_mask:0xf bank_mask:0xf bound_ctrl:1
	v_mov_b32_e32 v197, v196
	s_nop 1
	v_permlane16_swap_b32_e32 v196, v197
	v_add_f32_e32 v196, v196, v197
	v_pk_fma_f32 v[82:83], v[196:197], v[168:169], v[194:195] op_sel_hi:[0,1,1] neg_lo:[1,0,0] neg_hi:[1,0,0]
	ds_read_b64 v[188:189], v98
	s_waitcnt lgkmcnt(2)
	v_pk_mul_f32 v[190:191], v[82:83], v[174:175]
	v_add_f32_e32 v196, v190, v191
	v_pk_mul_f32 v[192:193], v[82:83], v[186:187]
	v_pk_mul_f32 v[194:195], v[82:83], v[176:177]
	v_add_f32_dpp v196, v196, v196 quad_perm:[1,0,3,2] row_mask:0xf bank_mask:0xf bound_ctrl:1
	v_add_f32_e32 v198, v192, v193
	v_pk_fma_f32 v[194:195], v[182:183], v[178:179], v[194:195] op_sel_hi:[0,1,1]
	v_add_f32_dpp v196, v196, v196 quad_perm:[2,3,0,1] row_mask:0xf bank_mask:0xf bound_ctrl:1
	v_add_f32_dpp v198, v198, v198 quad_perm:[1,0,3,2] row_mask:0xf bank_mask:0xf bound_ctrl:1
	ds_write_b32 v100, v198 offset:512
	v_add_f32_dpp v196, v196, v196 row_half_mirror row_mask:0xf bank_mask:0xf bound_ctrl:1
	s_nop 1
	v_add_f32_dpp v196, v196, v196 row_mirror row_mask:0xf bank_mask:0xf bound_ctrl:1
	v_mov_b32_e32 v197, v196
	s_nop 1
	v_permlane16_swap_b32_e32 v196, v197
	v_add_f32_e32 v196, v196, v197
	v_pk_fma_f32 v[82:83], v[196:197], v[180:181], v[194:195] op_sel_hi:[0,1,1] neg_lo:[1,0,0] neg_hi:[1,0,0]
	s_waitcnt lgkmcnt(1)
	v_pk_mul_f32 v[192:193], v[82:83], v[188:189]
	v_add_f32_e32 v198, v192, v193
	s_nop 1
	v_add_f32_dpp v198, v198, v198 quad_perm:[1,0,3,2] row_mask:0xf bank_mask:0xf bound_ctrl:1
	ds_write_b32 v100, v198
	s_branch .Lrs_post
.Lrs_fwd:
	ds_read2st64_b64 v[162:165], v98 offset0:48 offset1:32
	ds_read2st64_b64 v[166:169], v98 offset0:16 offset1:64
	ds_read_b32 v170, v99
	ds_read2st64_b64 v[174:177], v153 offset0:48 offset1:32
	ds_read2st64_b64 v[178:181], v153 offset0:16 offset1:64
	ds_read_b32 v182, v99 offset:64
	ds_read_b64 v[186:187], v98
	s_waitcnt lgkmcnt(4)
	v_pk_mul_f32 v[190:191], v[82:83], v[162:163]
	v_add_f32_e32 v196, v190, v191
	v_pk_mul_f32 v[194:195], v[82:83], v[164:165]
	s_nop 0
	v_add_f32_dpp v196, v196, v196 quad_perm:[1,0,3,2] row_mask:0xf bank_mask:0xf bound_ctrl:1
	v_pk_fma_f32 v[194:195], v[170:171], v[166:167], v[194:195] op_sel_hi:[0,1,1]
	s_nop 0
	v_add_f32_dpp v196, v196, v196 quad_perm:[2,3,0,1] row_mask:0xf bank_mask:0xf bound_ctrl:1
	s_nop 1
	v_add_f32_dpp v196, v196, v196 row_half_mirror row_mask:0xf bank_mask:0xf bound_ctrl:1
	s_nop 1
	v_add_f32_dpp v196, v196, v196 row_mirror row_mask:0xf bank_mask:0xf bound_ctrl:1
	v_mov_b32_e32 v197, v196
	s_nop 1
	v_permlane16_swap_b32_e32 v196, v197
	v_add_f32_e32 v196, v196, v197
	v_pk_fma_f32 v[82:83], v[196:197], v[168:169], v[194:195] op_sel_hi:[0,1,1] neg_lo:[1,0,0] neg_hi:[1,0,0]
	ds_read2st64_b64 v[162:165], v98 offset0:49 offset1:33
	ds_read2st64_b64 v[166:169], v98 offset0:17 offset1:65
	ds_read_b32 v170, v99 offset:128
	ds_read_b64 v[188:189], v98 offset:256
	s_waitcnt lgkmcnt(4)
	v_pk_mul_f32 v[190:191], v[82:83], v[174:175]
	v_add_f32_e32 v196, v190, v191
	v_pk_mul_f32 v[192:193], v[82:83], v[186:187]
	v_pk_mul_f32 v[194:195], v[82:83], v[176:177]
	v_add_f32_dpp v196, v196, v196 quad_perm:[1,0,3,2] row_mask:0xf bank_mask:0xf bound_ctrl:1
	v_add_f32_e32 v198, v192, v193
	v_pk_fma_f32 v[194:195], v[182:183], v[178:179], v[194:195] op_sel_hi:[0,1,1]
	v_add_f32_dpp v196, v196, v196 quad_perm:[2,3,0,1] row_mask:0xf bank_mask:0xf bound_ctrl:1
	v_add_f32_dpp v198, v198, v198 quad_perm:[1,0,3,2] row_mask:0xf bank_mask:0xf bound_ctrl:1
	ds_write_b32 v100, v198
	v_add_f32_dpp v196, v196, v196 row_half_mirror row_mask:0xf bank_mask:0xf bound_ctrl:1
	s_nop 1
	v_add_f32_dpp v196, v196, v196 row_mirror row_mask:0xf bank_mask:0xf bound_ctrl:1
	v_mov_b32_e32 v197, v196
	s_nop 1
	v_permlane16_swap_b32_e32 v196, v197
	v_add_f32_e32 v196, v196, v197
	v_pk_fma_f32 v[82:83], v[196:197], v[180:181], v[194:195] op_sel_hi:[0,1,1] neg_lo:[1,0,0] neg_hi:[1,0,0]
	ds_read2st64_b64 v[174:177], v153 offset0:49 offset1:33
	ds_read2st64_b64 v[178:181], v153 offset0:17 offset1:65
	ds_read_b32 v182, v99 offset:192
	ds_read_b64 v[186:187], v98 offset:512
	s_waitcnt lgkmcnt(5)
	v_pk_mul_f32 v[190:191], v[82:83], v[162:163]
	v_add_f32_e32 v196, v190, v191
	v_pk_mul_f32 v[192:193], v[82:83], v[188:189]
	v_pk_mul_f32 v[194:195], v[82:83], v[164:165]
	v_add_f32_dpp v196, v196, v196 quad_perm:[1,0,3,2] row_mask:0xf bank_mask:0xf bound_ctrl:1
	v_add_f32_e32 v198, v192, v193
	v_pk_fma_f32 v[194:195], v[170:171], v[166:167], v[194:195] op_sel_hi:[0,1,1]
	v_add_f32_dpp v196, v196, v196 quad_perm:[2,3,0,1] row_mask:0xf bank_mask:0xf bound_ctrl:1
	v_add_f32_dpp v198, v198, v198 quad_perm:[1,0,3,2] row_mask:0xf bank_mask:0xf bound_ctrl:1
	ds_write_b32 v100, v198 offset:512
	v_add_f32_dpp v196, v196, v196 row_half_mirror row_mask:0xf bank_mask:0xf bound_ctrl:1
	s_nop 1
	v_add_f32_dpp v196, v196, v196 row_mirror row_mask:0xf bank_mask:0xf bound_ctrl:1
	v_mov_b32_e32 v197, v196
	s_nop 1
	v_permlane16_swap_b32_e32 v196, v197
	v_add_f32_e32 v196, v196, v197
	v_pk_fma_f32 v[82:83], v[196:197], v[168:169], v[194:195] op_sel_hi:[0,1,1] neg_lo:[1,0,0] neg_hi:[1,0,0]
	ds_read2st64_b64 v[162:165], v98 offset0:50 offset1:34
	ds_read2st64_b64 v[166:169], v98 offset0:18 offset1:66
	ds_read_b32 v170, v99 offset:256
	ds_read_b64 v[188:189], v98 offset:768
	s_waitcnt lgkmcnt(5)
	v_pk_mul_f32 v[190:191], v[82:83], v[174:175]
	v_add_f32_e32 v196, v190, v191
	v_pk_mul_f32 v[192:193], v[82:83], v[186:187]
	v_pk_mul_f32 v[194:195], v[82:83], v[176:177]
	v_add_f32_dpp v196, v196, v196 quad_perm:[1,0,3,2] row_mask:0xf bank_mask:0xf bound_ctrl:1
	v_add_f32_e32 v198, v192, v193
	v_pk_fma_f32 v[194:195], v[182:183], v[178:179], v[194:195] op_sel_hi:[0,1,1]
	v_add_f32_dpp v196, v196, v196 quad_perm:[2,3,0,1] row_mask:0xf bank_mask:0xf bound_ctrl:1
	v_add_f32_dpp v198, v198, v198 quad_perm:[1,0,3,2] row_mask:0xf bank_mask:0xf bound_ctrl:1
	ds_write_b32 v100, v198 offset:1024
	v_add_f32_dpp v196, v196, v196 row_half_mirror row_mask:0xf bank_mask:0xf bound_ctrl:1
	s_nop 1
	v_add_f32_dpp v196, v196, v196 row_mirror row_mask:0xf bank_mask:0xf bound_ctrl:1
	v_mov_b32_e32 v197, v196
	s_nop 1
	v_permlane16_swap_b32_e32 v196, v197
	v_add_f32_e32 v196, v196, v197
	v_pk_fma_f32 v[82:83], v[196:197], v[180:181], v[194:195] op_sel_hi:[0,1,1] neg_lo:[1,0,0] neg_hi:[1,0,0]
	ds_read2st64_b64 v[174:177], v153 offset0:50 offset1:34
	ds_read2st64_b64 v[178:181], v153 offset0:18 offset1:66
	ds_read_b32 v182, v99 offset:320
	ds_read_b64 v[186:187], v98 offset:1024
	s_waitcnt lgkmcnt(5)
	v_pk_mul_f32 v[190:191], v[82:83], v[162:163]
	v_add_f32_e32 v196, v190, v191
	v_pk_mul_f32 v[192:193], v[82:83], v[188:189]
	v_pk_mul_f32 v[194:195], v[82:83], v[164:165]
	v_add_f32_dpp v196, v196, v196 quad_perm:[1,0,3,2] row_mask:0xf bank_mask:0xf bound_ctrl:1
	v_add_f32_e32 v198, v192, v193
	v_pk_fma_f32 v[194:195], v[170:171], v[166:167], v[194:195] op_sel_hi:[0,1,1]
	v_add_f32_dpp v196, v196, v196 quad_perm:[2,3,0,1] row_mask:0xf bank_mask:0xf bound_ctrl:1
	v_add_f32_dpp v198, v198, v198 quad_perm:[1,0,3,2] row_mask:0xf bank_mask:0xf bound_ctrl:1
	ds_write_b32 v100, v198 offset:1536
	v_add_f32_dpp v196, v196, v196 row_half_mirror row_mask:0xf bank_mask:0xf bound_ctrl:1
	s_nop 1
	v_add_f32_dpp v196, v196, v196 row_mirror row_mask:0xf bank_mask:0xf bound_ctrl:1
	v_mov_b32_e32 v197, v196
	s_nop 1
	v_permlane16_swap_b32_e32 v196, v197
	v_add_f32_e32 v196, v196, v197
	v_pk_fma_f32 v[82:83], v[196:197], v[168:169], v[194:195] op_sel_hi:[0,1,1] neg_lo:[1,0,0] neg_hi:[1,0,0]
	ds_read2st64_b64 v[162:165], v98 offset0:51 offset1:35
	ds_read2st64_b64 v[166:169], v98 offset0:19 offset1:67
	ds_read_b32 v170, v99 offset:384
	ds_read_b64 v[188:189], v98 offset:1280
	s_waitcnt lgkmcnt(5)
	v_pk_mul_f32 v[190:191], v[82:83], v[174:175]
	v_add_f32_e32 v196, v190, v191
	v_pk_mul_f32 v[192:193], v[82:83], v[186:187]
	v_pk_mul_f32 v[194:195], v[82:83], v[176:177]
	v_add_f32_dpp v196, v196, v196 quad_perm:[1,0,3,2] row_mask:0xf bank_mask:0xf bound_ctrl:1
	v_add_f32_e32 v198, v192, v193
	v_pk_fma_f32 v[194:195], v[182:183], v[178:179], v[194:195] op_sel_hi:[0,1,1]
	v_add_f32_dpp v196, v196, v196 quad_perm:[2,3,0,1] row_mask:0xf bank_mask:0xf bound_ctrl:1
	v_add_f32_dpp v198, v198, v198 quad_perm:[1,0,3,2] row_mask:0xf bank_mask:0xf bound_ctrl:1
	ds_write_b32 v100, v198 offset:2048
	v_add_f32_dpp v196, v196, v196 row_half_mirror row_mask:0xf bank_mask:0xf bound_ctrl:1
	s_nop 1
	v_add_f32_dpp v196, v196, v196 row_mirror row_mask:0xf bank_mask:0xf bound_ctrl:1
	v_mov_b32_e32 v197, v196
	s_nop 1
	v_permlane16_swap_b32_e32 v196, v197
	v_add_f32_e32 v196, v196, v197
	v_pk_fma_f32 v[82:83], v[196:197], v[180:181], v[194:195] op_sel_hi:[0,1,1] neg_lo:[1,0,0] neg_hi:[1,0,0]
	ds_read2st64_b64 v[174:177], v153 offset0:51 offset1:35
	ds_read2st64_b64 v[178:181], v153 offset0:19 offset1:67
	ds_read_b32 v182, v99 offset:448
	ds_read_b64 v[186:187], v98 offset:1536
	s_waitcnt lgkmcnt(5)
	v_pk_mul_f32 v[190:191], v[82:83], v[162:163]
	v_add_f32_e32 v196, v190, v191
	v_pk_mul_f32 v[192:193], v[82:83], v[188:189]
	v_pk_mul_f32 v[194:195], v[82:83], v[164:165]
	v_add_f32_dpp v196, v196, v196 quad_perm:[1,0,3,2] row_mask:0xf bank_mask:0xf bound_ctrl:1
	v_add_f32_e32 v198, v192, v193
	v_pk_fma_f32 v[194:195], v[170:171], v[166:167], v[194:195] op_sel_hi:[0,1,1]
	v_add_f32_dpp v196, v196, v196 quad_perm:[2,3,0,1] row_mask:0xf bank_mask:0xf bound_ctrl:1
	v_add_f32_dpp v198, v198, v198 quad_perm:[1,0,3,2] row_mask:0xf bank_mask:0xf bound_ctrl:1
	ds_write_b32 v100, v198 offset:2560
	v_add_f32_dpp v196, v196, v196 row_half_mirror row_mask:0xf bank_mask:0xf bound_ctrl:1
	s_nop 1
	v_add_f32_dpp v196, v196, v196 row_mirror row_mask:0xf bank_mask:0xf bound_ctrl:1
	v_mov_b32_e32 v197, v196
	s_nop 1
	v_permlane16_swap_b32_e32 v196, v197
	v_add_f32_e32 v196, v196, v197
	v_pk_fma_f32 v[82:83], v[196:197], v[168:169], v[194:195] op_sel_hi:[0,1,1] neg_lo:[1,0,0] neg_hi:[1,0,0]
	ds_read2st64_b64 v[162:165], v98 offset0:52 offset1:36
	ds_read2st64_b64 v[166:169], v98 offset0:20 offset1:68
	ds_read_b32 v170, v99 offset:512
	ds_read_b64 v[188:189], v98 offset:1792
	s_waitcnt lgkmcnt(5)
	v_pk_mul_f32 v[190:191], v[82:83], v[174:175]
	v_add_f32_e32 v196, v190, v191
	v_pk_mul_f32 v[192:193], v[82:83], v[186:187]
	v_pk_mul_f32 v[194:195], v[82:83], v[176:177]
	v_add_f32_dpp v196, v196, v196 quad_perm:[1,0,3,2] row_mask:0xf bank_mask:0xf bound_ctrl:1
	v_add_f32_e32 v198, v192, v193
	v_pk_fma_f32 v[194:195], v[182:183], v[178:179], v[194:195] op_sel_hi:[0,1,1]
	v_add_f32_dpp v196, v196, v196 quad_perm:[2,3,0,1] row_mask:0xf bank_mask:0xf bound_ctrl:1
	v_add_f32_dpp v198, v198, v198 quad_perm:[1,0,3,2] row_mask:0xf bank_mask:0xf bound_ctrl:1
	ds_write_b32 v100, v198 offset:3072
	v_add_f32_dpp v196, v196, v196 row_half_mirror row_mask:0xf bank_mask:0xf bound_ctrl:1
	s_nop 1
	v_add_f32_dpp v196, v196, v196 row_mirror row_mask:0xf bank_mask:0xf bound_ctrl:1
	v_mov_b32_e32 v197, v196
	s_nop 1
	v_permlane16_swap_b32_e32 v196, v197
	v_add_f32_e32 v196, v196, v197
	v_pk_fma_f32 v[82:83], v[196:197], v[180:181], v[194:195] op_sel_hi:[0,1,1] neg_lo:[1,0,0] neg_hi:[1,0,0]
	ds_read2st64_b64 v[174:177], v153 offset0:52 offset1:36
	ds_read2st64_b64 v[178:181], v153 offset0:20 offset1:68
	ds_read_b32 v182, v99 offset:576
	ds_read_b64 v[186:187], v98 offset:2048
	s_waitcnt lgkmcnt(5)
	v_pk_mul_f32 v[190:191], v[82:83], v[162:163]
	v_add_f32_e32 v196, v190, v191
	v_pk_mul_f32 v[192:193], v[82:83], v[188:189]
	v_pk_mul_f32 v[194:195], v[82:83], v[164:165]
	v_add_f32_dpp v196, v196, v196 quad_perm:[1,0,3,2] row_mask:0xf bank_mask:0xf bound_ctrl:1
	v_add_f32_e32 v198, v192, v193
	v_pk_fma_f32 v[194:195], v[170:171], v[166:167], v[194:195] op_sel_hi:[0,1,1]
	v_add_f32_dpp v196, v196, v196 quad_perm:[2,3,0,1] row_mask:0xf bank_mask:0xf bound_ctrl:1
	v_add_f32_dpp v198, v198, v198 quad_perm:[1,0,3,2] row_mask:0xf bank_mask:0xf bound_ctrl:1
	ds_write_b32 v100, v198 offset:3584
	v_add_f32_dpp v196, v196, v196 row_half_mirror row_mask:0xf bank_mask:0xf bound_ctrl:1
	s_nop 1
	v_add_f32_dpp v196, v196, v196 row_mirror row_mask:0xf bank_mask:0xf bound_ctrl:1
	v_mov_b32_e32 v197, v196
	s_nop 1
	v_permlane16_swap_b32_e32 v196, v197
	v_add_f32_e32 v196, v196, v197
	v_pk_fma_f32 v[82:83], v[196:197], v[168:169], v[194:195] op_sel_hi:[0,1,1] neg_lo:[1,0,0] neg_hi:[1,0,0]
	ds_read2st64_b64 v[162:165], v98 offset0:53 offset1:37
	ds_read2st64_b64 v[166:169], v98 offset0:21 offset1:69
	ds_read_b32 v170, v99 offset:640
	ds_read_b64 v[188:189], v98 offset:2304
	s_waitcnt lgkmcnt(5)
	v_pk_mul_f32 v[190:191], v[82:83], v[174:175]
	v_add_f32_e32 v196, v190, v191
	v_pk_mul_f32 v[192:193], v[82:83], v[186:187]
	v_pk_mul_f32 v[194:195], v[82:83], v[176:177]
	v_add_f32_dpp v196, v196, v196 quad_perm:[1,0,3,2] row_mask:0xf bank_mask:0xf bound_ctrl:1
	v_add_f32_e32 v198, v192, v193
	v_pk_fma_f32 v[194:195], v[182:183], v[178:179], v[194:195] op_sel_hi:[0,1,1]
	v_add_f32_dpp v196, v196, v196 quad_perm:[2,3,0,1] row_mask:0xf bank_mask:0xf bound_ctrl:1
	v_add_f32_dpp v198, v198, v198 quad_perm:[1,0,3,2] row_mask:0xf bank_mask:0xf bound_ctrl:1
	ds_write_b32 v100, v198 offset:4096
	v_add_f32_dpp v196, v196, v196 row_half_mirror row_mask:0xf bank_mask:0xf bound_ctrl:1
	s_nop 1
	v_add_f32_dpp v196, v196, v196 row_mirror row_mask:0xf bank_mask:0xf bound_ctrl:1
	v_mov_b32_e32 v197, v196
	s_nop 1
	v_permlane16_swap_b32_e32 v196, v197
	v_add_f32_e32 v196, v196, v197
	v_pk_fma_f32 v[82:83], v[196:197], v[180:181], v[194:195] op_sel_hi:[0,1,1] neg_lo:[1,0,0] neg_hi:[1,0,0]
	ds_read2st64_b64 v[174:177], v153 offset0:53 offset1:37
	ds_read2st64_b64 v[178:181], v153 offset0:21 offset1:69
	ds_read_b32 v182, v99 offset:704
	ds_read_b64 v[186:187], v98 offset:2560
	s_waitcnt lgkmcnt(5)
	v_pk_mul_f32 v[190:191], v[82:83], v[162:163]
	v_add_f32_e32 v196, v190, v191
	v_pk_mul_f32 v[192:193], v[82:83], v[188:189]
	v_pk_mul_f32 v[194:195], v[82:83], v[164:165]
	v_add_f32_dpp v196, v196, v196 quad_perm:[1,0,3,2] row_mask:0xf bank_mask:0xf bound_ctrl:1
	v_add_f32_e32 v198, v192, v193
	v_pk_fma_f32 v[194:195], v[170:171], v[166:167], v[194:195] op_sel_hi:[0,1,1]
	v_add_f32_dpp v196, v196, v196 quad_perm:[2,3,0,1] row_mask:0xf bank_mask:0xf bound_ctrl:1
	v_add_f32_dpp v198, v198, v198 quad_perm:[1,0,3,2] row_mask:0xf bank_mask:0xf bound_ctrl:1
	ds_write_b32 v100, v198 offset:4608
	v_add_f32_dpp v196, v196, v196 row_half_mirror row_mask:0xf bank_mask:0xf bound_ctrl:1
	s_nop 1
	v_add_f32_dpp v196, v196, v196 row_mirror row_mask:0xf bank_mask:0xf bound_ctrl:1
	v_mov_b32_e32 v197, v196
	s_nop 1
	v_permlane16_swap_b32_e32 v196, v197
	v_add_f32_e32 v196, v196, v197
	v_pk_fma_f32 v[82:83], v[196:197], v[168:169], v[194:195] op_sel_hi:[0,1,1] neg_lo:[1,0,0] neg_hi:[1,0,0]
	ds_read2st64_b64 v[162:165], v98 offset0:54 offset1:38
	ds_read2st64_b64 v[166:169], v98 offset0:22 offset1:70
	ds_read_b32 v170, v99 offset:768
	ds_read_b64 v[188:189], v98 offset:2816
	s_waitcnt lgkmcnt(5)
	v_pk_mul_f32 v[190:191], v[82:83], v[174:175]
	v_add_f32_e32 v196, v190, v191
	v_pk_mul_f32 v[192:193], v[82:83], v[186:187]
	v_pk_mul_f32 v[194:195], v[82:83], v[176:177]
	v_add_f32_dpp v196, v196, v196 quad_perm:[1,0,3,2] row_mask:0xf bank_mask:0xf bound_ctrl:1
	v_add_f32_e32 v198, v192, v193
	v_pk_fma_f32 v[194:195], v[182:183], v[178:179], v[194:195] op_sel_hi:[0,1,1]
	v_add_f32_dpp v196, v196, v196 quad_perm:[2,3,0,1] row_mask:0xf bank_mask:0xf bound_ctrl:1
	v_add_f32_dpp v198, v198, v198 quad_perm:[1,0,3,2] row_mask:0xf bank_mask:0xf bound_ctrl:1
	ds_write_b32 v100, v198 offset:5120
	v_add_f32_dpp v196, v196, v196 row_half_mirror row_mask:0xf bank_mask:0xf bound_ctrl:1
	s_nop 1
	v_add_f32_dpp v196, v196, v196 row_mirror row_mask:0xf bank_mask:0xf bound_ctrl:1
	v_mov_b32_e32 v197, v196
	s_nop 1
	v_permlane16_swap_b32_e32 v196, v197
	v_add_f32_e32 v196, v196, v197
	v_pk_fma_f32 v[82:83], v[196:197], v[180:181], v[194:195] op_sel_hi:[0,1,1] neg_lo:[1,0,0] neg_hi:[1,0,0]
	ds_read2st64_b64 v[174:177], v153 offset0:54 offset1:38
	ds_read2st64_b64 v[178:181], v153 offset0:22 offset1:70
	ds_read_b32 v182, v99 offset:832
	ds_read_b64 v[186:187], v98 offset:3072
	s_waitcnt lgkmcnt(5)
	v_pk_mul_f32 v[190:191], v[82:83], v[162:163]
	v_add_f32_e32 v196, v190, v191
	v_pk_mul_f32 v[192:193], v[82:83], v[188:189]
	v_pk_mul_f32 v[194:195], v[82:83], v[164:165]
	v_add_f32_dpp v196, v196, v196 quad_perm:[1,0,3,2] row_mask:0xf bank_mask:0xf bound_ctrl:1
	v_add_f32_e32 v198, v192, v193
	v_pk_fma_f32 v[194:195], v[170:171], v[166:167], v[194:195] op_sel_hi:[0,1,1]
	v_add_f32_dpp v196, v196, v196 quad_perm:[2,3,0,1] row_mask:0xf bank_mask:0xf bound_ctrl:1
	v_add_f32_dpp v198, v198, v198 quad_perm:[1,0,3,2] row_mask:0xf bank_mask:0xf bound_ctrl:1
	ds_write_b32 v100, v198 offset:5632
	v_add_f32_dpp v196, v196, v196 row_half_mirror row_mask:0xf bank_mask:0xf bound_ctrl:1
	s_nop 1
	v_add_f32_dpp v196, v196, v196 row_mirror row_mask:0xf bank_mask:0xf bound_ctrl:1
	v_mov_b32_e32 v197, v196
	s_nop 1
	v_permlane16_swap_b32_e32 v196, v197
	v_add_f32_e32 v196, v196, v197
	v_pk_fma_f32 v[82:83], v[196:197], v[168:169], v[194:195] op_sel_hi:[0,1,1] neg_lo:[1,0,0] neg_hi:[1,0,0]
	ds_read2st64_b64 v[162:165], v98 offset0:55 offset1:39
	ds_read2st64_b64 v[166:169], v98 offset0:23 offset1:71
	ds_read_b32 v170, v99 offset:896
	ds_read_b64 v[188:189], v98 offset:3328
	s_waitcnt lgkmcnt(5)
	v_pk_mul_f32 v[190:191], v[82:83], v[174:175]
	v_add_f32_e32 v196, v190, v191
	v_pk_mul_f32 v[192:193], v[82:83], v[186:187]
	v_pk_mul_f32 v[194:195], v[82:83], v[176:177]
	v_add_f32_dpp v196, v196, v196 quad_perm:[1,0,3,2] row_mask:0xf bank_mask:0xf bound_ctrl:1
	v_add_f32_e32 v198, v192, v193
	v_pk_fma_f32 v[194:195], v[182:183], v[178:179], v[194:195] op_sel_hi:[0,1,1]
	v_add_f32_dpp v196, v196, v196 quad_perm:[2,3,0,1] row_mask:0xf bank_mask:0xf bound_ctrl:1
	v_add_f32_dpp v198, v198, v198 quad_perm:[1,0,3,2] row_mask:0xf bank_mask:0xf bound_ctrl:1
	ds_write_b32 v100, v198 offset:6144
	v_add_f32_dpp v196, v196, v196 row_half_mirror row_mask:0xf bank_mask:0xf bound_ctrl:1
	s_nop 1
	v_add_f32_dpp v196, v196, v196 row_mirror row_mask:0xf bank_mask:0xf bound_ctrl:1
	v_mov_b32_e32 v197, v196
	s_nop 1
	v_permlane16_swap_b32_e32 v196, v197
	v_add_f32_e32 v196, v196, v197
	v_pk_fma_f32 v[82:83], v[196:197], v[180:181], v[194:195] op_sel_hi:[0,1,1] neg_lo:[1,0,0] neg_hi:[1,0,0]
	ds_read2st64_b64 v[174:177], v153 offset0:55 offset1:39
	ds_read2st64_b64 v[178:181], v153 offset0:23 offset1:71
	ds_read_b32 v182, v99 offset:960
	ds_read_b64 v[186:187], v98 offset:3584
	s_waitcnt lgkmcnt(5)
	v_pk_mul_f32 v[190:191], v[82:83], v[162:163]
	v_add_f32_e32 v196, v190, v191
	v_pk_mul_f32 v[192:193], v[82:83], v[188:189]
	v_pk_mul_f32 v[194:195], v[82:83], v[164:165]
	v_add_f32_dpp v196, v196, v196 quad_perm:[1,0,3,2] row_mask:0xf bank_mask:0xf bound_ctrl:1
	v_add_f32_e32 v198, v192, v193
	v_pk_fma_f32 v[194:195], v[170:171], v[166:167], v[194:195] op_sel_hi:[0,1,1]
	v_add_f32_dpp v196, v196, v196 quad_perm:[2,3,0,1] row_mask:0xf bank_mask:0xf bound_ctrl:1
	v_add_f32_dpp v198, v198, v198 quad_perm:[1,0,3,2] row_mask:0xf bank_mask:0xf bound_ctrl:1
	ds_write_b32 v100, v198 offset:6656
	v_add_f32_dpp v196, v196, v196 row_half_mirror row_mask:0xf bank_mask:0xf bound_ctrl:1
	s_nop 1
	v_add_f32_dpp v196, v196, v196 row_mirror row_mask:0xf bank_mask:0xf bound_ctrl:1
	v_mov_b32_e32 v197, v196
	s_nop 1
	v_permlane16_swap_b32_e32 v196, v197
	v_add_f32_e32 v196, v196, v197
	v_pk_fma_f32 v[82:83], v[196:197], v[168:169], v[194:195] op_sel_hi:[0,1,1] neg_lo:[1,0,0] neg_hi:[1,0,0]
	ds_read2st64_b64 v[162:165], v98 offset0:56 offset1:40
	ds_read2st64_b64 v[166:169], v98 offset0:24 offset1:72
	ds_read_b32 v170, v99 offset:1024
	ds_read_b64 v[188:189], v98 offset:3840
	s_waitcnt lgkmcnt(5)
	v_pk_mul_f32 v[190:191], v[82:83], v[174:175]
	v_add_f32_e32 v196, v190, v191
	v_pk_mul_f32 v[192:193], v[82:83], v[186:187]
	v_pk_mul_f32 v[194:195], v[82:83], v[176:177]
	v_add_f32_dpp v196, v196, v196 quad_perm:[1,0,3,2] row_mask:0xf bank_mask:0xf bound_ctrl:1
	v_add_f32_e32 v198, v192, v193
	v_pk_fma_f32 v[194:195], v[182:183], v[178:179], v[194:195] op_sel_hi:[0,1,1]
	v_add_f32_dpp v196, v196, v196 quad_perm:[2,3,0,1] row_mask:0xf bank_mask:0xf bound_ctrl:1
	v_add_f32_dpp v198, v198, v198 quad_perm:[1,0,3,2] row_mask:0xf bank_mask:0xf bound_ctrl:1
	ds_write_b32 v100, v198 offset:7168
	v_add_f32_dpp v196, v196, v196 row_half_mirror row_mask:0xf bank_mask:0xf bound_ctrl:1
	s_nop 1
	v_add_f32_dpp v196, v196, v196 row_mirror row_mask:0xf bank_mask:0xf bound_ctrl:1
	v_mov_b32_e32 v197, v196
	s_nop 1
	v_permlane16_swap_b32_e32 v196, v197
	v_add_f32_e32 v196, v196, v197
	v_pk_fma_f32 v[82:83], v[196:197], v[180:181], v[194:195] op_sel_hi:[0,1,1] neg_lo:[1,0,0] neg_hi:[1,0,0]
	ds_read2st64_b64 v[174:177], v153 offset0:56 offset1:40
	ds_read2st64_b64 v[178:181], v153 offset0:24 offset1:72
	ds_read_b32 v182, v99 offset:1088
	ds_read_b64 v[186:187], v98 offset:4096
	s_waitcnt lgkmcnt(5)
	v_pk_mul_f32 v[190:191], v[82:83], v[162:163]
	v_add_f32_e32 v196, v190, v191
	v_pk_mul_f32 v[192:193], v[82:83], v[188:189]
	v_pk_mul_f32 v[194:195], v[82:83], v[164:165]
	v_add_f32_dpp v196, v196, v196 quad_perm:[1,0,3,2] row_mask:0xf bank_mask:0xf bound_ctrl:1
	v_add_f32_e32 v198, v192, v193
	v_pk_fma_f32 v[194:195], v[170:171], v[166:167], v[194:195] op_sel_hi:[0,1,1]
	v_add_f32_dpp v196, v196, v196 quad_perm:[2,3,0,1] row_mask:0xf bank_mask:0xf bound_ctrl:1
	v_add_f32_dpp v198, v198, v198 quad_perm:[1,0,3,2] row_mask:0xf bank_mask:0xf bound_ctrl:1
	ds_write_b32 v100, v198 offset:7680
	v_add_f32_dpp v196, v196, v196 row_half_mirror row_mask:0xf bank_mask:0xf bound_ctrl:1
	s_nop 1
	v_add_f32_dpp v196, v196, v196 row_mirror row_mask:0xf bank_mask:0xf bound_ctrl:1
	v_mov_b32_e32 v197, v196
	s_nop 1
	v_permlane16_swap_b32_e32 v196, v197
	v_add_f32_e32 v196, v196, v197
	v_pk_fma_f32 v[82:83], v[196:197], v[168:169], v[194:195] op_sel_hi:[0,1,1] neg_lo:[1,0,0] neg_hi:[1,0,0]
	ds_read2st64_b64 v[162:165], v98 offset0:57 offset1:41
	ds_read2st64_b64 v[166:169], v98 offset0:25 offset1:73
	ds_read_b32 v170, v99 offset:1152
	ds_read_b64 v[188:189], v98 offset:4352
	s_waitcnt lgkmcnt(5)
	v_pk_mul_f32 v[190:191], v[82:83], v[174:175]
	v_add_f32_e32 v196, v190, v191
	v_pk_mul_f32 v[192:193], v[82:83], v[186:187]
	v_pk_mul_f32 v[194:195], v[82:83], v[176:177]
	v_add_f32_dpp v196, v196, v196 quad_perm:[1,0,3,2] row_mask:0xf bank_mask:0xf bound_ctrl:1
	v_add_f32_e32 v198, v192, v193
	v_pk_fma_f32 v[194:195], v[182:183], v[178:179], v[194:195] op_sel_hi:[0,1,1]
	v_add_f32_dpp v196, v196, v196 quad_perm:[2,3,0,1] row_mask:0xf bank_mask:0xf bound_ctrl:1
	v_add_f32_dpp v198, v198, v198 quad_perm:[1,0,3,2] row_mask:0xf bank_mask:0xf bound_ctrl:1
	ds_write_b32 v100, v198 offset:8192
	v_add_f32_dpp v196, v196, v196 row_half_mirror row_mask:0xf bank_mask:0xf bound_ctrl:1
	s_nop 1
	v_add_f32_dpp v196, v196, v196 row_mirror row_mask:0xf bank_mask:0xf bound_ctrl:1
	v_mov_b32_e32 v197, v196
	s_nop 1
	v_permlane16_swap_b32_e32 v196, v197
	v_add_f32_e32 v196, v196, v197
	v_pk_fma_f32 v[82:83], v[196:197], v[180:181], v[194:195] op_sel_hi:[0,1,1] neg_lo:[1,0,0] neg_hi:[1,0,0]
	ds_read2st64_b64 v[174:177], v153 offset0:57 offset1:41
	ds_read2st64_b64 v[178:181], v153 offset0:25 offset1:73
	ds_read_b32 v182, v99 offset:1216
	ds_read_b64 v[186:187], v98 offset:4608
	s_waitcnt lgkmcnt(5)
	v_pk_mul_f32 v[190:191], v[82:83], v[162:163]
	v_add_f32_e32 v196, v190, v191
	v_pk_mul_f32 v[192:193], v[82:83], v[188:189]
	v_pk_mul_f32 v[194:195], v[82:83], v[164:165]
	v_add_f32_dpp v196, v196, v196 quad_perm:[1,0,3,2] row_mask:0xf bank_mask:0xf bound_ctrl:1
	v_add_f32_e32 v198, v192, v193
	v_pk_fma_f32 v[194:195], v[170:171], v[166:167], v[194:195] op_sel_hi:[0,1,1]
	v_add_f32_dpp v196, v196, v196 quad_perm:[2,3,0,1] row_mask:0xf bank_mask:0xf bound_ctrl:1
	v_add_f32_dpp v198, v198, v198 quad_perm:[1,0,3,2] row_mask:0xf bank_mask:0xf bound_ctrl:1
	ds_write_b32 v100, v198 offset:8704
	v_add_f32_dpp v196, v196, v196 row_half_mirror row_mask:0xf bank_mask:0xf bound_ctrl:1
	s_nop 1
	v_add_f32_dpp v196, v196, v196 row_mirror row_mask:0xf bank_mask:0xf bound_ctrl:1
	v_mov_b32_e32 v197, v196
	s_nop 1
	v_permlane16_swap_b32_e32 v196, v197
	v_add_f32_e32 v196, v196, v197
	v_pk_fma_f32 v[82:83], v[196:197], v[168:169], v[194:195] op_sel_hi:[0,1,1] neg_lo:[1,0,0] neg_hi:[1,0,0]
	ds_read2st64_b64 v[162:165], v98 offset0:58 offset1:42
	ds_read2st64_b64 v[166:169], v98 offset0:26 offset1:74
	ds_read_b32 v170, v99 offset:1280
	ds_read_b64 v[188:189], v98 offset:4864
	s_waitcnt lgkmcnt(5)
	v_pk_mul_f32 v[190:191], v[82:83], v[174:175]
	v_add_f32_e32 v196, v190, v191
	v_pk_mul_f32 v[192:193], v[82:83], v[186:187]
	v_pk_mul_f32 v[194:195], v[82:83], v[176:177]
	v_add_f32_dpp v196, v196, v196 quad_perm:[1,0,3,2] row_mask:0xf bank_mask:0xf bound_ctrl:1
	v_add_f32_e32 v198, v192, v193
	v_pk_fma_f32 v[194:195], v[182:183], v[178:179], v[194:195] op_sel_hi:[0,1,1]
	v_add_f32_dpp v196, v196, v196 quad_perm:[2,3,0,1] row_mask:0xf bank_mask:0xf bound_ctrl:1
	v_add_f32_dpp v198, v198, v198 quad_perm:[1,0,3,2] row_mask:0xf bank_mask:0xf bound_ctrl:1
	ds_write_b32 v100, v198 offset:9216
	v_add_f32_dpp v196, v196, v196 row_half_mirror row_mask:0xf bank_mask:0xf bound_ctrl:1
	s_nop 1
	v_add_f32_dpp v196, v196, v196 row_mirror row_mask:0xf bank_mask:0xf bound_ctrl:1
	v_mov_b32_e32 v197, v196
	s_nop 1
	v_permlane16_swap_b32_e32 v196, v197
	v_add_f32_e32 v196, v196, v197
	v_pk_fma_f32 v[82:83], v[196:197], v[180:181], v[194:195] op_sel_hi:[0,1,1] neg_lo:[1,0,0] neg_hi:[1,0,0]
	ds_read2st64_b64 v[174:177], v153 offset0:58 offset1:42
	ds_read2st64_b64 v[178:181], v153 offset0:26 offset1:74
	ds_read_b32 v182, v99 offset:1344
	ds_read_b64 v[186:187], v98 offset:5120
	s_waitcnt lgkmcnt(5)
	v_pk_mul_f32 v[190:191], v[82:83], v[162:163]
	v_add_f32_e32 v196, v190, v191
	v_pk_mul_f32 v[192:193], v[82:83], v[188:189]
	v_pk_mul_f32 v[194:195], v[82:83], v[164:165]
	v_add_f32_dpp v196, v196, v196 quad_perm:[1,0,3,2] row_mask:0xf bank_mask:0xf bound_ctrl:1
	v_add_f32_e32 v198, v192, v193
	v_pk_fma_f32 v[194:195], v[170:171], v[166:167], v[194:195] op_sel_hi:[0,1,1]
	v_add_f32_dpp v196, v196, v196 quad_perm:[2,3,0,1] row_mask:0xf bank_mask:0xf bound_ctrl:1
	v_add_f32_dpp v198, v198, v198 quad_perm:[1,0,3,2] row_mask:0xf bank_mask:0xf bound_ctrl:1
	ds_write_b32 v100, v198 offset:9728
	v_add_f32_dpp v196, v196, v196 row_half_mirror row_mask:0xf bank_mask:0xf bound_ctrl:1
	s_nop 1
	v_add_f32_dpp v196, v196, v196 row_mirror row_mask:0xf bank_mask:0xf bound_ctrl:1
	v_mov_b32_e32 v197, v196
	s_nop 1
	v_permlane16_swap_b32_e32 v196, v197
	v_add_f32_e32 v196, v196, v197
	v_pk_fma_f32 v[82:83], v[196:197], v[168:169], v[194:195] op_sel_hi:[0,1,1] neg_lo:[1,0,0] neg_hi:[1,0,0]
	ds_read2st64_b64 v[162:165], v98 offset0:59 offset1:43
	ds_read2st64_b64 v[166:169], v98 offset0:27 offset1:75
	ds_read_b32 v170, v99 offset:1408
	ds_read_b64 v[188:189], v98 offset:5376
	s_waitcnt lgkmcnt(5)
	v_pk_mul_f32 v[190:191], v[82:83], v[174:175]
	v_add_f32_e32 v196, v190, v191
	v_pk_mul_f32 v[192:193], v[82:83], v[186:187]
	v_pk_mul_f32 v[194:195], v[82:83], v[176:177]
	v_add_f32_dpp v196, v196, v196 quad_perm:[1,0,3,2] row_mask:0xf bank_mask:0xf bound_ctrl:1
	v_add_f32_e32 v198, v192, v193
	v_pk_fma_f32 v[194:195], v[182:183], v[178:179], v[194:195] op_sel_hi:[0,1,1]
	v_add_f32_dpp v196, v196, v196 quad_perm:[2,3,0,1] row_mask:0xf bank_mask:0xf bound_ctrl:1
	v_add_f32_dpp v198, v198, v198 quad_perm:[1,0,3,2] row_mask:0xf bank_mask:0xf bound_ctrl:1
	ds_write_b32 v100, v198 offset:10240
	v_add_f32_dpp v196, v196, v196 row_half_mirror row_mask:0xf bank_mask:0xf bound_ctrl:1
	s_nop 1
	v_add_f32_dpp v196, v196, v196 row_mirror row_mask:0xf bank_mask:0xf bound_ctrl:1
	v_mov_b32_e32 v197, v196
	s_nop 1
	v_permlane16_swap_b32_e32 v196, v197
	v_add_f32_e32 v196, v196, v197
	v_pk_fma_f32 v[82:83], v[196:197], v[180:181], v[194:195] op_sel_hi:[0,1,1] neg_lo:[1,0,0] neg_hi:[1,0,0]
	ds_read2st64_b64 v[174:177], v153 offset0:59 offset1:43
	ds_read2st64_b64 v[178:181], v153 offset0:27 offset1:75
	ds_read_b32 v182, v99 offset:1472
	ds_read_b64 v[186:187], v98 offset:5632
	s_waitcnt lgkmcnt(5)
	v_pk_mul_f32 v[190:191], v[82:83], v[162:163]
	v_add_f32_e32 v196, v190, v191
	v_pk_mul_f32 v[192:193], v[82:83], v[188:189]
	v_pk_mul_f32 v[194:195], v[82:83], v[164:165]
	v_add_f32_dpp v196, v196, v196 quad_perm:[1,0,3,2] row_mask:0xf bank_mask:0xf bound_ctrl:1
	v_add_f32_e32 v198, v192, v193
	v_pk_fma_f32 v[194:195], v[170:171], v[166:167], v[194:195] op_sel_hi:[0,1,1]
	v_add_f32_dpp v196, v196, v196 quad_perm:[2,3,0,1] row_mask:0xf bank_mask:0xf bound_ctrl:1
	v_add_f32_dpp v198, v198, v198 quad_perm:[1,0,3,2] row_mask:0xf bank_mask:0xf bound_ctrl:1
	ds_write_b32 v100, v198 offset:10752
	v_add_f32_dpp v196, v196, v196 row_half_mirror row_mask:0xf bank_mask:0xf bound_ctrl:1
	s_nop 1
	v_add_f32_dpp v196, v196, v196 row_mirror row_mask:0xf bank_mask:0xf bound_ctrl:1
	v_mov_b32_e32 v197, v196
	s_nop 1
	v_permlane16_swap_b32_e32 v196, v197
	v_add_f32_e32 v196, v196, v197
	v_pk_fma_f32 v[82:83], v[196:197], v[168:169], v[194:195] op_sel_hi:[0,1,1] neg_lo:[1,0,0] neg_hi:[1,0,0]
	ds_read2st64_b64 v[162:165], v98 offset0:60 offset1:44
	ds_read2st64_b64 v[166:169], v98 offset0:28 offset1:76
	ds_read_b32 v170, v99 offset:1536
	ds_read_b64 v[188:189], v98 offset:5888
	s_waitcnt lgkmcnt(5)
	v_pk_mul_f32 v[190:191], v[82:83], v[174:175]
	v_add_f32_e32 v196, v190, v191
	v_pk_mul_f32 v[192:193], v[82:83], v[186:187]
	v_pk_mul_f32 v[194:195], v[82:83], v[176:177]
	v_add_f32_dpp v196, v196, v196 quad_perm:[1,0,3,2] row_mask:0xf bank_mask:0xf bound_ctrl:1
	v_add_f32_e32 v198, v192, v193
	v_pk_fma_f32 v[194:195], v[182:183], v[178:179], v[194:195] op_sel_hi:[0,1,1]
	v_add_f32_dpp v196, v196, v196 quad_perm:[2,3,0,1] row_mask:0xf bank_mask:0xf bound_ctrl:1
	v_add_f32_dpp v198, v198, v198 quad_perm:[1,0,3,2] row_mask:0xf bank_mask:0xf bound_ctrl:1
	ds_write_b32 v100, v198 offset:11264
	v_add_f32_dpp v196, v196, v196 row_half_mirror row_mask:0xf bank_mask:0xf bound_ctrl:1
	s_nop 1
	v_add_f32_dpp v196, v196, v196 row_mirror row_mask:0xf bank_mask:0xf bound_ctrl:1
	v_mov_b32_e32 v197, v196
	s_nop 1
	v_permlane16_swap_b32_e32 v196, v197
	v_add_f32_e32 v196, v196, v197
	v_pk_fma_f32 v[82:83], v[196:197], v[180:181], v[194:195] op_sel_hi:[0,1,1] neg_lo:[1,0,0] neg_hi:[1,0,0]
	ds_read2st64_b64 v[174:177], v153 offset0:60 offset1:44
	ds_read2st64_b64 v[178:181], v153 offset0:28 offset1:76
	ds_read_b32 v182, v99 offset:1600
	ds_read_b64 v[186:187], v98 offset:6144
	s_waitcnt lgkmcnt(5)
	v_pk_mul_f32 v[190:191], v[82:83], v[162:163]
	v_add_f32_e32 v196, v190, v191
	v_pk_mul_f32 v[192:193], v[82:83], v[188:189]
	v_pk_mul_f32 v[194:195], v[82:83], v[164:165]
	v_add_f32_dpp v196, v196, v196 quad_perm:[1,0,3,2] row_mask:0xf bank_mask:0xf bound_ctrl:1
	v_add_f32_e32 v198, v192, v193
	v_pk_fma_f32 v[194:195], v[170:171], v[166:167], v[194:195] op_sel_hi:[0,1,1]
	v_add_f32_dpp v196, v196, v196 quad_perm:[2,3,0,1] row_mask:0xf bank_mask:0xf bound_ctrl:1
	v_add_f32_dpp v198, v198, v198 quad_perm:[1,0,3,2] row_mask:0xf bank_mask:0xf bound_ctrl:1
	ds_write_b32 v100, v198 offset:11776
	v_add_f32_dpp v196, v196, v196 row_half_mirror row_mask:0xf bank_mask:0xf bound_ctrl:1
	s_nop 1
	v_add_f32_dpp v196, v196, v196 row_mirror row_mask:0xf bank_mask:0xf bound_ctrl:1
	v_mov_b32_e32 v197, v196
	s_nop 1
	v_permlane16_swap_b32_e32 v196, v197
	v_add_f32_e32 v196, v196, v197
	v_pk_fma_f32 v[82:83], v[196:197], v[168:169], v[194:195] op_sel_hi:[0,1,1] neg_lo:[1,0,0] neg_hi:[1,0,0]
	ds_read2st64_b64 v[162:165], v98 offset0:61 offset1:45
	ds_read2st64_b64 v[166:169], v98 offset0:29 offset1:77
	ds_read_b32 v170, v99 offset:1664
	ds_read_b64 v[188:189], v98 offset:6400
	s_waitcnt lgkmcnt(5)
	v_pk_mul_f32 v[190:191], v[82:83], v[174:175]
	v_add_f32_e32 v196, v190, v191
	v_pk_mul_f32 v[192:193], v[82:83], v[186:187]
	v_pk_mul_f32 v[194:195], v[82:83], v[176:177]
	v_add_f32_dpp v196, v196, v196 quad_perm:[1,0,3,2] row_mask:0xf bank_mask:0xf bound_ctrl:1
	v_add_f32_e32 v198, v192, v193
	v_pk_fma_f32 v[194:195], v[182:183], v[178:179], v[194:195] op_sel_hi:[0,1,1]
	v_add_f32_dpp v196, v196, v196 quad_perm:[2,3,0,1] row_mask:0xf bank_mask:0xf bound_ctrl:1
	v_add_f32_dpp v198, v198, v198 quad_perm:[1,0,3,2] row_mask:0xf bank_mask:0xf bound_ctrl:1
	ds_write_b32 v100, v198 offset:12288
	v_add_f32_dpp v196, v196, v196 row_half_mirror row_mask:0xf bank_mask:0xf bound_ctrl:1
	s_nop 1
	v_add_f32_dpp v196, v196, v196 row_mirror row_mask:0xf bank_mask:0xf bound_ctrl:1
	v_mov_b32_e32 v197, v196
	s_nop 1
	v_permlane16_swap_b32_e32 v196, v197
	v_add_f32_e32 v196, v196, v197
	v_pk_fma_f32 v[82:83], v[196:197], v[180:181], v[194:195] op_sel_hi:[0,1,1] neg_lo:[1,0,0] neg_hi:[1,0,0]
	ds_read2st64_b64 v[174:177], v153 offset0:61 offset1:45
	ds_read2st64_b64 v[178:181], v153 offset0:29 offset1:77
	ds_read_b32 v182, v99 offset:1728
	ds_read_b64 v[186:187], v98 offset:6656
	s_waitcnt lgkmcnt(5)
	v_pk_mul_f32 v[190:191], v[82:83], v[162:163]
	v_add_f32_e32 v196, v190, v191
	v_pk_mul_f32 v[192:193], v[82:83], v[188:189]
	v_pk_mul_f32 v[194:195], v[82:83], v[164:165]
	v_add_f32_dpp v196, v196, v196 quad_perm:[1,0,3,2] row_mask:0xf bank_mask:0xf bound_ctrl:1
	v_add_f32_e32 v198, v192, v193
	v_pk_fma_f32 v[194:195], v[170:171], v[166:167], v[194:195] op_sel_hi:[0,1,1]
	v_add_f32_dpp v196, v196, v196 quad_perm:[2,3,0,1] row_mask:0xf bank_mask:0xf bound_ctrl:1
	v_add_f32_dpp v198, v198, v198 quad_perm:[1,0,3,2] row_mask:0xf bank_mask:0xf bound_ctrl:1
	ds_write_b32 v100, v198 offset:12800
	v_add_f32_dpp v196, v196, v196 row_half_mirror row_mask:0xf bank_mask:0xf bound_ctrl:1
	s_nop 1
	v_add_f32_dpp v196, v196, v196 row_mirror row_mask:0xf bank_mask:0xf bound_ctrl:1
	v_mov_b32_e32 v197, v196
	s_nop 1
	v_permlane16_swap_b32_e32 v196, v197
	v_add_f32_e32 v196, v196, v197
	v_pk_fma_f32 v[82:83], v[196:197], v[168:169], v[194:195] op_sel_hi:[0,1,1] neg_lo:[1,0,0] neg_hi:[1,0,0]
	ds_read2st64_b64 v[162:165], v98 offset0:62 offset1:46
	ds_read2st64_b64 v[166:169], v98 offset0:30 offset1:78
	ds_read_b32 v170, v99 offset:1792
	ds_read_b64 v[188:189], v98 offset:6912
	s_waitcnt lgkmcnt(5)
	v_pk_mul_f32 v[190:191], v[82:83], v[174:175]
	v_add_f32_e32 v196, v190, v191
	v_pk_mul_f32 v[192:193], v[82:83], v[186:187]
	v_pk_mul_f32 v[194:195], v[82:83], v[176:177]
	v_add_f32_dpp v196, v196, v196 quad_perm:[1,0,3,2] row_mask:0xf bank_mask:0xf bound_ctrl:1
	v_add_f32_e32 v198, v192, v193
	v_pk_fma_f32 v[194:195], v[182:183], v[178:179], v[194:195] op_sel_hi:[0,1,1]
	v_add_f32_dpp v196, v196, v196 quad_perm:[2,3,0,1] row_mask:0xf bank_mask:0xf bound_ctrl:1
	v_add_f32_dpp v198, v198, v198 quad_perm:[1,0,3,2] row_mask:0xf bank_mask:0xf bound_ctrl:1
	ds_write_b32 v100, v198 offset:13312
	v_add_f32_dpp v196, v196, v196 row_half_mirror row_mask:0xf bank_mask:0xf bound_ctrl:1
	s_nop 1
	v_add_f32_dpp v196, v196, v196 row_mirror row_mask:0xf bank_mask:0xf bound_ctrl:1
	v_mov_b32_e32 v197, v196
	s_nop 1
	v_permlane16_swap_b32_e32 v196, v197
	v_add_f32_e32 v196, v196, v197
	v_pk_fma_f32 v[82:83], v[196:197], v[180:181], v[194:195] op_sel_hi:[0,1,1] neg_lo:[1,0,0] neg_hi:[1,0,0]
	ds_read2st64_b64 v[174:177], v153 offset0:62 offset1:46
	ds_read2st64_b64 v[178:181], v153 offset0:30 offset1:78
	ds_read_b32 v182, v99 offset:1856
	ds_read_b64 v[186:187], v98 offset:7168
	s_waitcnt lgkmcnt(5)
	v_pk_mul_f32 v[190:191], v[82:83], v[162:163]
	v_add_f32_e32 v196, v190, v191
	v_pk_mul_f32 v[192:193], v[82:83], v[188:189]
	v_pk_mul_f32 v[194:195], v[82:83], v[164:165]
	v_add_f32_dpp v196, v196, v196 quad_perm:[1,0,3,2] row_mask:0xf bank_mask:0xf bound_ctrl:1
	v_add_f32_e32 v198, v192, v193
	v_pk_fma_f32 v[194:195], v[170:171], v[166:167], v[194:195] op_sel_hi:[0,1,1]
	v_add_f32_dpp v196, v196, v196 quad_perm:[2,3,0,1] row_mask:0xf bank_mask:0xf bound_ctrl:1
	v_add_f32_dpp v198, v198, v198 quad_perm:[1,0,3,2] row_mask:0xf bank_mask:0xf bound_ctrl:1
	ds_write_b32 v100, v198 offset:13824
	v_add_f32_dpp v196, v196, v196 row_half_mirror row_mask:0xf bank_mask:0xf bound_ctrl:1
	s_nop 1
	v_add_f32_dpp v196, v196, v196 row_mirror row_mask:0xf bank_mask:0xf bound_ctrl:1
	v_mov_b32_e32 v197, v196
	s_nop 1
	v_permlane16_swap_b32_e32 v196, v197
	v_add_f32_e32 v196, v196, v197
	v_pk_fma_f32 v[82:83], v[196:197], v[168:169], v[194:195] op_sel_hi:[0,1,1] neg_lo:[1,0,0] neg_hi:[1,0,0]
	ds_read2st64_b64 v[162:165], v98 offset0:63 offset1:47
	ds_read2st64_b64 v[166:169], v98 offset0:31 offset1:79
	ds_read_b32 v170, v99 offset:1920
	ds_read_b64 v[188:189], v98 offset:7424
	s_waitcnt lgkmcnt(5)
	v_pk_mul_f32 v[190:191], v[82:83], v[174:175]
	v_add_f32_e32 v196, v190, v191
	v_pk_mul_f32 v[192:193], v[82:83], v[186:187]
	v_pk_mul_f32 v[194:195], v[82:83], v[176:177]
	v_add_f32_dpp v196, v196, v196 quad_perm:[1,0,3,2] row_mask:0xf bank_mask:0xf bound_ctrl:1
	v_add_f32_e32 v198, v192, v193
	v_pk_fma_f32 v[194:195], v[182:183], v[178:179], v[194:195] op_sel_hi:[0,1,1]
	v_add_f32_dpp v196, v196, v196 quad_perm:[2,3,0,1] row_mask:0xf bank_mask:0xf bound_ctrl:1
	v_add_f32_dpp v198, v198, v198 quad_perm:[1,0,3,2] row_mask:0xf bank_mask:0xf bound_ctrl:1
	ds_write_b32 v100, v198 offset:14336
	v_add_f32_dpp v196, v196, v196 row_half_mirror row_mask:0xf bank_mask:0xf bound_ctrl:1
	s_nop 1
	v_add_f32_dpp v196, v196, v196 row_mirror row_mask:0xf bank_mask:0xf bound_ctrl:1
	v_mov_b32_e32 v197, v196
	s_nop 1
	v_permlane16_swap_b32_e32 v196, v197
	v_add_f32_e32 v196, v196, v197
	v_pk_fma_f32 v[82:83], v[196:197], v[180:181], v[194:195] op_sel_hi:[0,1,1] neg_lo:[1,0,0] neg_hi:[1,0,0]
	ds_read2st64_b64 v[174:177], v153 offset0:63 offset1:47
	ds_read2st64_b64 v[178:181], v153 offset0:31 offset1:79
	ds_read_b32 v182, v99 offset:1984
	ds_read_b64 v[186:187], v98 offset:7680
	s_waitcnt lgkmcnt(5)
	v_pk_mul_f32 v[190:191], v[82:83], v[162:163]
	v_add_f32_e32 v196, v190, v191
	v_pk_mul_f32 v[192:193], v[82:83], v[188:189]
	v_pk_mul_f32 v[194:195], v[82:83], v[164:165]
	v_add_f32_dpp v196, v196, v196 quad_perm:[1,0,3,2] row_mask:0xf bank_mask:0xf bound_ctrl:1
	v_add_f32_e32 v198, v192, v193
	v_pk_fma_f32 v[194:195], v[170:171], v[166:167], v[194:195] op_sel_hi:[0,1,1]
	v_add_f32_dpp v196, v196, v196 quad_perm:[2,3,0,1] row_mask:0xf bank_mask:0xf bound_ctrl:1
	v_add_f32_dpp v198, v198, v198 quad_perm:[1,0,3,2] row_mask:0xf bank_mask:0xf bound_ctrl:1
	ds_write_b32 v100, v198 offset:14848
	v_add_f32_dpp v196, v196, v196 row_half_mirror row_mask:0xf bank_mask:0xf bound_ctrl:1
	s_nop 1
	v_add_f32_dpp v196, v196, v196 row_mirror row_mask:0xf bank_mask:0xf bound_ctrl:1
	v_mov_b32_e32 v197, v196
	s_nop 1
	v_permlane16_swap_b32_e32 v196, v197
	v_add_f32_e32 v196, v196, v197
	v_pk_fma_f32 v[82:83], v[196:197], v[168:169], v[194:195] op_sel_hi:[0,1,1] neg_lo:[1,0,0] neg_hi:[1,0,0]
	ds_read_b64 v[188:189], v98 offset:7936
	s_waitcnt lgkmcnt(2)
	v_pk_mul_f32 v[190:191], v[82:83], v[174:175]
	v_add_f32_e32 v196, v190, v191
	v_pk_mul_f32 v[192:193], v[82:83], v[186:187]
	v_pk_mul_f32 v[194:195], v[82:83], v[176:177]
	v_add_f32_dpp v196, v196, v196 quad_perm:[1,0,3,2] row_mask:0xf bank_mask:0xf bound_ctrl:1
	v_add_f32_e32 v198, v192, v193
	v_pk_fma_f32 v[194:195], v[182:183], v[178:179], v[194:195] op_sel_hi:[0,1,1]
	v_add_f32_dpp v196, v196, v196 quad_perm:[2,3,0,1] row_mask:0xf bank_mask:0xf bound_ctrl:1
	v_add_f32_dpp v198, v198, v198 quad_perm:[1,0,3,2] row_mask:0xf bank_mask:0xf bound_ctrl:1
	ds_write_b32 v100, v198 offset:15360
	v_add_f32_dpp v196, v196, v196 row_half_mirror row_mask:0xf bank_mask:0xf bound_ctrl:1
	s_nop 1
	v_add_f32_dpp v196, v196, v196 row_mirror row_mask:0xf bank_mask:0xf bound_ctrl:1
	v_mov_b32_e32 v197, v196
	s_nop 1
	v_permlane16_swap_b32_e32 v196, v197
	v_add_f32_e32 v196, v196, v197
	v_pk_fma_f32 v[82:83], v[196:197], v[180:181], v[194:195] op_sel_hi:[0,1,1] neg_lo:[1,0,0] neg_hi:[1,0,0]
	s_waitcnt lgkmcnt(1)
	v_pk_mul_f32 v[192:193], v[82:83], v[188:189]
	v_add_f32_e32 v198, v192, v193
	s_nop 1
	v_add_f32_dpp v198, v198, v198 quad_perm:[1,0,3,2] row_mask:0xf bank_mask:0xf bound_ctrl:1
	ds_write_b32 v100, v198 offset:15872
